# write-through stores also in the P1 epilogue (on top of P2 / P3-late-tile write-through)
# baseline (speedup 1.0000x reference)
; __device__ __forceinline__ u32x4 pack8(const f32x4 a, const f32x4 b) { u32x4 w; w.x = cvt_pk_bf16(a[0], a[1]); w.y = cvt_pk_bf16(a[2], a[3]); w.z = cvt_pk_bf16(b[0], b[1]); w.w = cvt_pk_bf16(b[2], b[3]); return w; }
;     __device__ __forceinline__ void operator()(const f32x4 (&acc)[2][2][4][2], const Unit& u, int wr, int wc, int fr, int fq) const {
;     ...
;         if (pn >= 16) {
; #pragma unroll
;             for (int ai = 0; ai < 2; ++ai)
; #pragma unroll
;                 for (int m = 0; m < 4; ++m) { const int r = row0 + ai * HALF + m * 16;
;                     f32x4 ra[2], gb[2];
; #pragma unroll
;                     for (int n = 0; n < 2; ++n)
; #pragma unroll
;                         for (int i = 0; i < 4; ++i) { const float ea = __expf(-acc[ai][0][m][n][i]), eb = __expf(-fmaxf(acc[ai][1][m][n][i], -60.f));
;                             gb[n][i] = __builtin_amdgcn_rcpf(1.f + eb); ra[n][i] = (1.f + eb) * __builtin_amdgcn_rcpf(1.f + ea); }
;                     bf16_t* gp = gab + (size_t)r * 2048 + (pn - 16) * 128 + c8;
;                     *(u32x4*)gp = pack8(ra[0], ra[1]); *(u32x4*)(gp + 1024) = pack8(gb[0], gb[1]); }
.LBB0_141:
	s_and_b64 vcc, exec, s[10:11]
	s_cbranch_vccz .LBB0_258
	v_mul_f32_e32 v126, 0xbfb8aa3b, v126
	v_mul_f32_e32 v127, 0xbfb8aa3b, v127
	v_exp_f32_e32 v126, v126
	v_exp_f32_e32 v127, v127
	v_max_f32_e32 v122, v122, v122
	v_max_f32_e32 v123, v123, v123
	v_max_f32_e32 v122, 0xc2700000, v122
	v_max_f32_e32 v123, 0xc2700000, v123
	v_mul_f32_e32 v122, 0xbfb8aa3b, v122
	v_mul_f32_e32 v123, 0xbfb8aa3b, v123
	v_exp_f32_e32 v122, v122
	v_add_f32_e32 v126, 1.0, v126
	v_exp_f32_e32 v123, v123
	v_add_f32_e32 v127, 1.0, v127
	v_rcp_f32_e32 v126, v126
	v_rcp_f32_e32 v127, v127
	v_pk_add_f32 v[122:123], v[122:123], 1.0 op_sel_hi:[1,0]
	v_mul_f32_e32 v118, 0xbfb8aa3b, v118
	v_rcp_f32_e32 v132, v122
	v_rcp_f32_e32 v133, v123
	v_pk_mul_f32 v[122:123], v[126:127], v[122:123]
	v_mul_f32_e32 v126, 0xbfb8aa3b, v128
	v_mul_f32_e32 v127, 0xbfb8aa3b, v129
	v_mul_f32_e32 v119, 0xbfb8aa3b, v119
	v_exp_f32_e32 v126, v126
	v_exp_f32_e32 v127, v127
	v_exp_f32_e32 v118, v118
	v_exp_f32_e32 v119, v119
	v_mul_f32_e32 v120, 0xbfb8aa3b, v120
	v_mul_f32_e32 v121, 0xbfb8aa3b, v121
	v_max_f32_e32 v124, v124, v124
	v_max_f32_e32 v125, v125, v125
	v_max_f32_e32 v114, v114, v114
	v_max_f32_e32 v115, v115, v115
	v_exp_f32_e32 v120, v120
	v_exp_f32_e32 v121, v121
	v_max_f32_e32 v124, 0xc2700000, v124
	v_max_f32_e32 v125, 0xc2700000, v125
	v_max_f32_e32 v114, 0xc2700000, v114
	v_max_f32_e32 v115, 0xc2700000, v115
	v_max_f32_e32 v116, v116, v116
	v_max_f32_e32 v117, v117, v117
	v_mul_f32_e32 v124, 0xbfb8aa3b, v124
	v_mul_f32_e32 v125, 0xbfb8aa3b, v125
	v_mul_f32_e32 v114, 0xbfb8aa3b, v114
	v_mul_f32_e32 v115, 0xbfb8aa3b, v115
	v_max_f32_e32 v116, 0xc2700000, v116
	v_max_f32_e32 v117, 0xc2700000, v117
	v_exp_f32_e32 v124, v124
	v_add_f32_e32 v126, 1.0, v126
	v_exp_f32_e32 v125, v125
	v_add_f32_e32 v127, 1.0, v127
	v_exp_f32_e32 v114, v114
	v_add_f32_e32 v118, 1.0, v118
	v_exp_f32_e32 v115, v115
	v_add_f32_e32 v119, 1.0, v119
	v_mul_f32_e32 v116, 0xbfb8aa3b, v116
	v_mul_f32_e32 v117, 0xbfb8aa3b, v117
	v_rcp_f32_e32 v126, v126
	v_rcp_f32_e32 v127, v127
	v_rcp_f32_e32 v118, v118
	v_rcp_f32_e32 v119, v119
	v_exp_f32_e32 v116, v116
	v_add_f32_e32 v120, 1.0, v120
	v_exp_f32_e32 v117, v117
	v_add_f32_e32 v121, 1.0, v121
	v_mul_f32_e32 v110, 0xbfb8aa3b, v110
	v_mul_f32_e32 v111, 0xbfb8aa3b, v111
	v_rcp_f32_e32 v120, v120
	v_rcp_f32_e32 v121, v121
	v_exp_f32_e32 v110, v110
	v_exp_f32_e32 v111, v111
	v_max_f32_e32 v106, v106, v106
	v_max_f32_e32 v107, v107, v107
	v_or_b32_e32 v130, s49, v1
	v_pk_add_f32 v[124:125], v[124:125], 1.0 op_sel_hi:[1,0]
	v_pk_add_f32 v[114:115], v[114:115], 1.0 op_sel_hi:[1,0]
	v_max_f32_e32 v106, 0xc2700000, v106
	v_max_f32_e32 v107, 0xc2700000, v107
	s_lshl_b32 s4, s96, 7
	v_rcp_f32_e32 v128, v124
	v_rcp_f32_e32 v129, v125
	v_pk_mul_f32 v[124:125], v[126:127], v[124:125]
	v_rcp_f32_e32 v126, v114
	v_rcp_f32_e32 v127, v115
	v_pk_mul_f32 v[118:119], v[118:119], v[114:115]
	v_pk_add_f32 v[114:115], v[116:117], 1.0 op_sel_hi:[1,0]
	v_ashrrev_i32_e32 v131, 31, v130
	v_mul_f32_e32 v106, 0xbfb8aa3b, v106
	v_mul_f32_e32 v107, 0xbfb8aa3b, v107
	s_add_i32 s38, s4, 0xfffff800
	v_rcp_f32_e32 v134, v114
	v_pk_mul_f32 v[120:121], v[120:121], v[114:115]
	v_rcp_f32_e32 v135, v115
	v_lshlrev_b64 v[114:115], 12, v[130:131]
	v_exp_f32_e32 v106, v106
	v_add_f32_e32 v110, 1.0, v110
	v_exp_f32_e32 v107, v107
	v_add_f32_e32 v111, 1.0, v111
	v_lshl_add_u64 v[114:115], s[54:55], 0, v[114:115]
	s_lshl_b64 s[10:11], s[38:39], 1
	v_rcp_f32_e32 v110, v110
	v_rcp_f32_e32 v111, v111
	v_lshl_add_u64 v[114:115], v[114:115], 0, s[10:11]
	v_lshlrev_b32_e32 v146, 1, v158
	v_lshl_add_u64 v[114:115], v[114:115], 0, v[146:147]
	v_cvt_pk_bf16_f32 v116, v122, v123
	v_cvt_pk_bf16_f32 v117, v124, v125
	v_cvt_pk_bf16_f32 v118, v118, v119
	v_cvt_pk_bf16_f32 v119, v120, v121
	global_store_dwordx4 v[114:115], v[116:119], off sc1
	v_pk_add_f32 v[106:107], v[106:107], 1.0 op_sel_hi:[1,0]
	v_mul_f32_e32 v102, 0xbfb8aa3b, v102
	v_cvt_pk_bf16_f32 v116, v132, v133
	v_cvt_pk_bf16_f32 v117, v128, v129
	v_cvt_pk_bf16_f32 v118, v126, v127
	v_cvt_pk_bf16_f32 v119, v134, v135
	global_store_dwordx4 v[114:115], v[116:119], off offset:2048 sc1
	v_pk_mul_f32 v[110:111], v[110:111], v[106:107]
	v_mul_f32_e32 v103, 0xbfb8aa3b, v103
	v_rcp_f32_e32 v116, v106
	v_mul_f32_e32 v106, 0xbfb8aa3b, v112
	v_exp_f32_e32 v106, v106
	v_exp_f32_e32 v102, v102
	v_exp_f32_e32 v103, v103
	v_max_f32_e32 v108, v108, v108
	v_add_f32_e32 v106, 1.0, v106
	v_rcp_f32_e32 v112, v106
	v_mul_f32_e32 v106, 0xbfb8aa3b, v113
	v_exp_f32_e32 v106, v106
	v_max_f32_e32 v109, v109, v109
	v_max_f32_e32 v98, v98, v98
	v_max_f32_e32 v99, v99, v99
	v_max_f32_e32 v108, 0xc2700000, v108
	v_max_f32_e32 v109, 0xc2700000, v109
	v_max_f32_e32 v98, 0xc2700000, v98
	v_max_f32_e32 v99, 0xc2700000, v99
	v_mul_f32_e32 v108, 0xbfb8aa3b, v108
	v_mul_f32_e32 v109, 0xbfb8aa3b, v109
	v_mul_f32_e32 v98, 0xbfb8aa3b, v98
	v_mul_f32_e32 v99, 0xbfb8aa3b, v99
	v_exp_f32_e32 v108, v108
	v_exp_f32_e32 v109, v109
	v_add_f32_e32 v106, 1.0, v106
	v_exp_f32_e32 v98, v98
	v_add_f32_e32 v102, 1.0, v102
	v_exp_f32_e32 v99, v99
	v_add_f32_e32 v103, 1.0, v103
	v_rcp_f32_e32 v113, v106
	v_rcp_f32_e32 v102, v102
	v_rcp_f32_e32 v103, v103
	v_rcp_f32_e32 v117, v107
	v_pk_add_f32 v[106:107], v[108:109], 1.0 op_sel_hi:[1,0]
	v_pk_add_f32 v[98:99], v[98:99], 1.0 op_sel_hi:[1,0]
	v_pk_mul_f32 v[108:109], v[112:113], v[106:107]
	v_rcp_f32_e32 v113, v98
	v_pk_mul_f32 v[102:103], v[102:103], v[98:99]
	v_mul_f32_e32 v98, 0xbfb8aa3b, v104
	v_exp_f32_e32 v98, v98
	v_max_f32_e32 v100, v100, v100
	v_max_f32_e32 v101, v101, v101
	v_max_f32_e32 v100, 0xc2700000, v100
	v_add_f32_e32 v98, 1.0, v98
; __device__ __forceinline__ u32x4 pack8(const f32x4 a, const f32x4 b) { u32x4 w; w.x = cvt_pk_bf16(a[0], a[1]); w.y = cvt_pk_bf16(a[2], a[3]); w.z = cvt_pk_bf16(b[0], b[1]); w.w = cvt_pk_bf16(b[2], b[3]); return w; }
;     __device__ __forceinline__ void operator()(const f32x4 (&acc)[2][2][4][2], const Unit& u, int wr, int wc, int fr, int fq) const {
;     ...
;         if (pn >= 16) {
; #pragma unroll
;             for (int ai = 0; ai < 2; ++ai)
; #pragma unroll
;                 for (int m = 0; m < 4; ++m) { const int r = row0 + ai * HALF + m * 16;
;                     f32x4 ra[2], gb[2];
; #pragma unroll
;                     for (int n = 0; n < 2; ++n)
; #pragma unroll
;                         for (int i = 0; i < 4; ++i) { const float ea = __expf(-acc[ai][0][m][n][i]), eb = __expf(-fmaxf(acc[ai][1][m][n][i], -60.f));
;                             gb[n][i] = __builtin_amdgcn_rcpf(1.f + eb); ra[n][i] = (1.f + eb) * __builtin_amdgcn_rcpf(1.f + ea); }
;                     bf16_t* gp = gab + (size_t)r * 2048 + (pn - 16) * 128 + c8;
;                     *(u32x4*)gp = pack8(ra[0], ra[1]); *(u32x4*)(gp + 1024) = pack8(gb[0], gb[1]); }
	v_rcp_f32_e32 v104, v98
	v_mul_f32_e32 v98, 0xbfb8aa3b, v105
	v_exp_f32_e32 v98, v98
	v_max_f32_e32 v101, 0xc2700000, v101
	v_mul_f32_e32 v100, 0xbfb8aa3b, v100
	v_mul_f32_e32 v101, 0xbfb8aa3b, v101
	v_exp_f32_e32 v100, v100
	v_exp_f32_e32 v101, v101
	v_add_f32_e32 v98, 1.0, v98
	v_rcp_f32_e32 v105, v98
	v_mul_f32_e32 v94, 0xbfb8aa3b, v94
	v_mul_f32_e32 v95, 0xbfb8aa3b, v95
	v_exp_f32_e32 v94, v94
	v_exp_f32_e32 v95, v95
	v_rcp_f32_e32 v119, v99
	v_pk_add_f32 v[98:99], v[100:101], 1.0 op_sel_hi:[1,0]
	v_max_f32_e32 v90, v90, v90
	v_max_f32_e32 v91, v91, v91
	v_rcp_f32_e32 v120, v98
	v_pk_mul_f32 v[104:105], v[104:105], v[98:99]
	v_or_b32_e32 v98, 16, v130
	v_max_f32_e32 v90, 0xc2700000, v90
	v_max_f32_e32 v91, 0xc2700000, v91
	v_rcp_f32_e32 v121, v99
	v_ashrrev_i32_e32 v99, 31, v98
	v_mul_f32_e32 v90, 0xbfb8aa3b, v90
	v_mul_f32_e32 v91, 0xbfb8aa3b, v91
	v_rcp_f32_e32 v118, v106
	v_rcp_f32_e32 v112, v107
	v_lshlrev_b64 v[98:99], 12, v[98:99]
	v_exp_f32_e32 v90, v90
	v_add_f32_e32 v94, 1.0, v94
	v_exp_f32_e32 v91, v91
	v_add_f32_e32 v95, 1.0, v95
	v_lshl_add_u64 v[98:99], s[54:55], 0, v[98:99]
	v_rcp_f32_e32 v94, v94
	v_rcp_f32_e32 v95, v95
	v_lshl_add_u64 v[98:99], v[98:99], 0, s[10:11]
	v_lshl_add_u64 v[106:107], v[98:99], 0, v[146:147]
	v_cvt_pk_bf16_f32 v98, v110, v111
	v_cvt_pk_bf16_f32 v99, v108, v109
	v_cvt_pk_bf16_f32 v100, v102, v103
	v_cvt_pk_bf16_f32 v101, v104, v105
	global_store_dwordx4 v[106:107], v[98:101], off sc1
	v_pk_add_f32 v[90:91], v[90:91], 1.0 op_sel_hi:[1,0]
	v_mul_f32_e32 v86, 0xbfb8aa3b, v86
	v_cvt_pk_bf16_f32 v98, v116, v117
	v_cvt_pk_bf16_f32 v99, v118, v112
	v_cvt_pk_bf16_f32 v100, v113, v119
	v_cvt_pk_bf16_f32 v101, v120, v121
	global_store_dwordx4 v[106:107], v[98:101], off offset:2048 sc1
	v_pk_mul_f32 v[94:95], v[94:95], v[90:91]
	v_mul_f32_e32 v87, 0xbfb8aa3b, v87
	v_rcp_f32_e32 v98, v90
	v_mul_f32_e32 v90, 0xbfb8aa3b, v96
	v_exp_f32_e32 v90, v90
	v_exp_f32_e32 v86, v86
	v_exp_f32_e32 v87, v87
	v_max_f32_e32 v92, v92, v92
	v_add_f32_e32 v90, 1.0, v90
	v_rcp_f32_e32 v96, v90
	v_mul_f32_e32 v90, 0xbfb8aa3b, v97
	v_exp_f32_e32 v90, v90
	v_max_f32_e32 v93, v93, v93
	v_max_f32_e32 v82, v82, v82
	v_max_f32_e32 v83, v83, v83
	v_max_f32_e32 v92, 0xc2700000, v92
	v_max_f32_e32 v93, 0xc2700000, v93
	v_max_f32_e32 v82, 0xc2700000, v82
	v_max_f32_e32 v83, 0xc2700000, v83
	v_mul_f32_e32 v92, 0xbfb8aa3b, v92
	v_mul_f32_e32 v93, 0xbfb8aa3b, v93
	v_mul_f32_e32 v82, 0xbfb8aa3b, v82
	v_mul_f32_e32 v83, 0xbfb8aa3b, v83
	v_exp_f32_e32 v92, v92
	v_exp_f32_e32 v93, v93
	v_add_f32_e32 v90, 1.0, v90
	v_exp_f32_e32 v82, v82
	v_add_f32_e32 v86, 1.0, v86
	v_exp_f32_e32 v83, v83
	v_add_f32_e32 v87, 1.0, v87
	v_rcp_f32_e32 v97, v90
	v_rcp_f32_e32 v86, v86
	v_rcp_f32_e32 v87, v87
	v_rcp_f32_e32 v99, v91
	v_pk_add_f32 v[90:91], v[92:93], 1.0 op_sel_hi:[1,0]
	v_pk_add_f32 v[82:83], v[82:83], 1.0 op_sel_hi:[1,0]
	v_pk_mul_f32 v[92:93], v[96:97], v[90:91]
	v_rcp_f32_e32 v97, v82
	v_pk_mul_f32 v[86:87], v[86:87], v[82:83]
	v_mul_f32_e32 v82, 0xbfb8aa3b, v88
	v_exp_f32_e32 v82, v82
	v_max_f32_e32 v84, v84, v84
	v_max_f32_e32 v85, v85, v85
	v_max_f32_e32 v84, 0xc2700000, v84
	v_add_f32_e32 v82, 1.0, v82
	v_rcp_f32_e32 v88, v82
	v_mul_f32_e32 v82, 0xbfb8aa3b, v89
	v_exp_f32_e32 v82, v82
	v_max_f32_e32 v85, 0xc2700000, v85
	v_mul_f32_e32 v84, 0xbfb8aa3b, v84
	v_mul_f32_e32 v85, 0xbfb8aa3b, v85
	v_exp_f32_e32 v84, v84
	v_exp_f32_e32 v85, v85
	v_add_f32_e32 v82, 1.0, v82
	v_rcp_f32_e32 v89, v82
	v_mul_f32_e32 v78, 0xbfb8aa3b, v78
	v_mul_f32_e32 v79, 0xbfb8aa3b, v79
	v_exp_f32_e32 v78, v78
	v_exp_f32_e32 v79, v79
	v_rcp_f32_e32 v101, v83
	v_pk_add_f32 v[82:83], v[84:85], 1.0 op_sel_hi:[1,0]
	v_max_f32_e32 v74, v74, v74
	v_max_f32_e32 v75, v75, v75
	v_rcp_f32_e32 v102, v82
	v_pk_mul_f32 v[88:89], v[88:89], v[82:83]
	v_or_b32_e32 v82, 32, v130
	v_max_f32_e32 v74, 0xc2700000, v74
	v_max_f32_e32 v75, 0xc2700000, v75
	v_rcp_f32_e32 v103, v83
	v_ashrrev_i32_e32 v83, 31, v82
	v_mul_f32_e32 v74, 0xbfb8aa3b, v74
	v_mul_f32_e32 v75, 0xbfb8aa3b, v75
	v_rcp_f32_e32 v100, v90
	v_rcp_f32_e32 v96, v91
	v_lshlrev_b64 v[82:83], 12, v[82:83]
	v_exp_f32_e32 v74, v74
	v_add_f32_e32 v78, 1.0, v78
	v_exp_f32_e32 v75, v75
	v_add_f32_e32 v79, 1.0, v79
	v_lshl_add_u64 v[82:83], s[54:55], 0, v[82:83]
	v_rcp_f32_e32 v78, v78
	v_rcp_f32_e32 v79, v79
	v_lshl_add_u64 v[82:83], v[82:83], 0, s[10:11]
	v_lshl_add_u64 v[90:91], v[82:83], 0, v[146:147]
	v_cvt_pk_bf16_f32 v82, v94, v95
	v_cvt_pk_bf16_f32 v83, v92, v93
	v_cvt_pk_bf16_f32 v84, v86, v87
	v_cvt_pk_bf16_f32 v85, v88, v89
	global_store_dwordx4 v[90:91], v[82:85], off sc1
	v_pk_add_f32 v[74:75], v[74:75], 1.0 op_sel_hi:[1,0]
	v_mul_f32_e32 v70, 0xbfb8aa3b, v70
	v_cvt_pk_bf16_f32 v82, v98, v99
	v_cvt_pk_bf16_f32 v83, v100, v96
	v_cvt_pk_bf16_f32 v84, v97, v101
	v_cvt_pk_bf16_f32 v85, v102, v103
	global_store_dwordx4 v[90:91], v[82:85], off offset:2048 sc1
	v_pk_mul_f32 v[78:79], v[78:79], v[74:75]
	v_mul_f32_e32 v71, 0xbfb8aa3b, v71
	v_rcp_f32_e32 v82, v74
	v_mul_f32_e32 v74, 0xbfb8aa3b, v80
	v_exp_f32_e32 v74, v74
	v_exp_f32_e32 v70, v70
	v_exp_f32_e32 v71, v71
	v_max_f32_e32 v76, v76, v76
	v_add_f32_e32 v74, 1.0, v74
	v_rcp_f32_e32 v80, v74
	v_mul_f32_e32 v74, 0xbfb8aa3b, v81
	v_exp_f32_e32 v74, v74
	v_max_f32_e32 v77, v77, v77
	v_max_f32_e32 v66, v66, v66
	v_max_f32_e32 v67, v67, v67
	v_max_f32_e32 v76, 0xc2700000, v76
	v_max_f32_e32 v77, 0xc2700000, v77
	v_max_f32_e32 v66, 0xc2700000, v66
	v_max_f32_e32 v67, 0xc2700000, v67
	v_mul_f32_e32 v76, 0xbfb8aa3b, v76
	v_mul_f32_e32 v77, 0xbfb8aa3b, v77
	v_mul_f32_e32 v66, 0xbfb8aa3b, v66
	v_mul_f32_e32 v67, 0xbfb8aa3b, v67
	v_exp_f32_e32 v76, v76
	v_exp_f32_e32 v77, v77
; __device__ __forceinline__ u32x4 pack8(const f32x4 a, const f32x4 b) { u32x4 w; w.x = cvt_pk_bf16(a[0], a[1]); w.y = cvt_pk_bf16(a[2], a[3]); w.z = cvt_pk_bf16(b[0], b[1]); w.w = cvt_pk_bf16(b[2], b[3]); return w; }
;     __device__ __forceinline__ void operator()(const f32x4 (&acc)[2][2][4][2], const Unit& u, int wr, int wc, int fr, int fq) const {
;     ...
;         if (pn >= 16) {
; #pragma unroll
;             for (int ai = 0; ai < 2; ++ai)
; #pragma unroll
;                 for (int m = 0; m < 4; ++m) { const int r = row0 + ai * HALF + m * 16;
;                     f32x4 ra[2], gb[2];
; #pragma unroll
;                     for (int n = 0; n < 2; ++n)
; #pragma unroll
;                         for (int i = 0; i < 4; ++i) { const float ea = __expf(-acc[ai][0][m][n][i]), eb = __expf(-fmaxf(acc[ai][1][m][n][i], -60.f));
;                             gb[n][i] = __builtin_amdgcn_rcpf(1.f + eb); ra[n][i] = (1.f + eb) * __builtin_amdgcn_rcpf(1.f + ea); }
;                     bf16_t* gp = gab + (size_t)r * 2048 + (pn - 16) * 128 + c8;
;                     *(u32x4*)gp = pack8(ra[0], ra[1]); *(u32x4*)(gp + 1024) = pack8(gb[0], gb[1]); }
	v_add_f32_e32 v74, 1.0, v74
	v_exp_f32_e32 v66, v66
	v_add_f32_e32 v70, 1.0, v70
	v_exp_f32_e32 v67, v67
	v_add_f32_e32 v71, 1.0, v71
	v_rcp_f32_e32 v81, v74
	v_rcp_f32_e32 v70, v70
	v_rcp_f32_e32 v71, v71
	v_rcp_f32_e32 v83, v75
	v_pk_add_f32 v[74:75], v[76:77], 1.0 op_sel_hi:[1,0]
	v_pk_add_f32 v[66:67], v[66:67], 1.0 op_sel_hi:[1,0]
	v_pk_mul_f32 v[76:77], v[80:81], v[74:75]
	v_rcp_f32_e32 v81, v66
	v_pk_mul_f32 v[70:71], v[70:71], v[66:67]
	v_mul_f32_e32 v66, 0xbfb8aa3b, v72
	v_exp_f32_e32 v66, v66
	v_max_f32_e32 v68, v68, v68
	v_max_f32_e32 v69, v69, v69
	v_max_f32_e32 v68, 0xc2700000, v68
	v_add_f32_e32 v66, 1.0, v66
	v_rcp_f32_e32 v72, v66
	v_mul_f32_e32 v66, 0xbfb8aa3b, v73
	v_exp_f32_e32 v66, v66
	v_max_f32_e32 v69, 0xc2700000, v69
	v_mul_f32_e32 v68, 0xbfb8aa3b, v68
	v_mul_f32_e32 v69, 0xbfb8aa3b, v69
	v_exp_f32_e32 v68, v68
	v_exp_f32_e32 v69, v69
	v_add_f32_e32 v66, 1.0, v66
	v_rcp_f32_e32 v73, v66
	v_mul_f32_e32 v62, 0xbfb8aa3b, v62
	v_mul_f32_e32 v63, 0xbfb8aa3b, v63
	v_exp_f32_e32 v62, v62
	v_exp_f32_e32 v63, v63
	v_rcp_f32_e32 v85, v67
	v_pk_add_f32 v[66:67], v[68:69], 1.0 op_sel_hi:[1,0]
	v_max_f32_e32 v58, v58, v58
	v_max_f32_e32 v59, v59, v59
	v_rcp_f32_e32 v86, v66
	v_pk_mul_f32 v[72:73], v[72:73], v[66:67]
	v_or_b32_e32 v66, 48, v130
	v_max_f32_e32 v58, 0xc2700000, v58
	v_max_f32_e32 v59, 0xc2700000, v59
	v_rcp_f32_e32 v87, v67
	v_ashrrev_i32_e32 v67, 31, v66
	v_mul_f32_e32 v58, 0xbfb8aa3b, v58
	v_mul_f32_e32 v59, 0xbfb8aa3b, v59
	v_rcp_f32_e32 v84, v74
	v_rcp_f32_e32 v80, v75
	v_lshlrev_b64 v[66:67], 12, v[66:67]
	v_exp_f32_e32 v58, v58
	v_add_f32_e32 v62, 1.0, v62
	v_exp_f32_e32 v59, v59
	v_add_f32_e32 v63, 1.0, v63
	v_lshl_add_u64 v[66:67], s[54:55], 0, v[66:67]
	v_rcp_f32_e32 v62, v62
	v_rcp_f32_e32 v63, v63
	v_lshl_add_u64 v[66:67], v[66:67], 0, s[10:11]
	v_lshl_add_u64 v[74:75], v[66:67], 0, v[146:147]
	v_cvt_pk_bf16_f32 v66, v78, v79
	v_cvt_pk_bf16_f32 v67, v76, v77
	v_cvt_pk_bf16_f32 v68, v70, v71
	v_cvt_pk_bf16_f32 v69, v72, v73
	global_store_dwordx4 v[74:75], v[66:69], off sc1
	v_pk_add_f32 v[58:59], v[58:59], 1.0 op_sel_hi:[1,0]
	v_mul_f32_e32 v54, 0xbfb8aa3b, v54
	v_cvt_pk_bf16_f32 v66, v82, v83
	v_cvt_pk_bf16_f32 v67, v84, v80
	v_cvt_pk_bf16_f32 v68, v81, v85
	v_cvt_pk_bf16_f32 v69, v86, v87
	global_store_dwordx4 v[74:75], v[66:69], off offset:2048 sc1
	v_pk_mul_f32 v[62:63], v[62:63], v[58:59]
	v_mul_f32_e32 v55, 0xbfb8aa3b, v55
	v_rcp_f32_e32 v66, v58
	v_mul_f32_e32 v58, 0xbfb8aa3b, v64
	v_exp_f32_e32 v58, v58
	v_exp_f32_e32 v54, v54
	v_exp_f32_e32 v55, v55
	v_max_f32_e32 v60, v60, v60
	v_add_f32_e32 v58, 1.0, v58
	v_rcp_f32_e32 v64, v58
	v_mul_f32_e32 v58, 0xbfb8aa3b, v65
	v_exp_f32_e32 v58, v58
	v_max_f32_e32 v61, v61, v61
	v_max_f32_e32 v50, v50, v50
	v_max_f32_e32 v51, v51, v51
	v_max_f32_e32 v60, 0xc2700000, v60
	v_max_f32_e32 v61, 0xc2700000, v61
	v_max_f32_e32 v50, 0xc2700000, v50
	v_max_f32_e32 v51, 0xc2700000, v51
	v_mul_f32_e32 v60, 0xbfb8aa3b, v60
	v_mul_f32_e32 v61, 0xbfb8aa3b, v61
	v_mul_f32_e32 v50, 0xbfb8aa3b, v50
	v_mul_f32_e32 v51, 0xbfb8aa3b, v51
	v_exp_f32_e32 v60, v60
	v_exp_f32_e32 v61, v61
	v_add_f32_e32 v58, 1.0, v58
	v_exp_f32_e32 v50, v50
	v_add_f32_e32 v54, 1.0, v54
	v_exp_f32_e32 v51, v51
	v_add_f32_e32 v55, 1.0, v55
	v_rcp_f32_e32 v65, v58
	v_rcp_f32_e32 v54, v54
	v_rcp_f32_e32 v55, v55
	v_rcp_f32_e32 v67, v59
	v_pk_add_f32 v[58:59], v[60:61], 1.0 op_sel_hi:[1,0]
	v_pk_add_f32 v[50:51], v[50:51], 1.0 op_sel_hi:[1,0]
	v_pk_mul_f32 v[60:61], v[64:65], v[58:59]
	v_rcp_f32_e32 v65, v50
	v_pk_mul_f32 v[54:55], v[54:55], v[50:51]
	v_mul_f32_e32 v50, 0xbfb8aa3b, v56
	v_exp_f32_e32 v50, v50
	v_max_f32_e32 v52, v52, v52
	v_max_f32_e32 v53, v53, v53
	v_max_f32_e32 v52, 0xc2700000, v52
	v_add_f32_e32 v50, 1.0, v50
	v_rcp_f32_e32 v56, v50
	v_mul_f32_e32 v50, 0xbfb8aa3b, v57
	v_exp_f32_e32 v50, v50
	v_max_f32_e32 v53, 0xc2700000, v53
	v_mul_f32_e32 v52, 0xbfb8aa3b, v52
	v_mul_f32_e32 v53, 0xbfb8aa3b, v53
	v_exp_f32_e32 v52, v52
	v_exp_f32_e32 v53, v53
	v_mul_f32_e32 v46, 0xbfb8aa3b, v46
	v_mul_f32_e32 v47, 0xbfb8aa3b, v47
	v_exp_f32_e32 v46, v46
	v_exp_f32_e32 v47, v47
	v_add_f32_e32 v50, 1.0, v50
	v_max_f32_e32 v42, v42, v42
	v_max_f32_e32 v43, v43, v43
	v_rcp_f32_e32 v57, v50
	v_max_f32_e32 v42, 0xc2700000, v42
	v_max_f32_e32 v43, 0xc2700000, v43
	v_rcp_f32_e32 v69, v51
	v_pk_add_f32 v[50:51], v[52:53], 1.0 op_sel_hi:[1,0]
	v_mul_f32_e32 v42, 0xbfb8aa3b, v42
	v_mul_f32_e32 v43, 0xbfb8aa3b, v43
	v_rcp_f32_e32 v68, v58
	v_rcp_f32_e32 v64, v59
	v_rcp_f32_e32 v70, v50
	v_rcp_f32_e32 v71, v51
	v_exp_f32_e32 v42, v42
	v_add_f32_e32 v46, 1.0, v46
	v_exp_f32_e32 v43, v43
	v_add_f32_e32 v47, 1.0, v47
	s_mov_b32 s4, 0x80000
	v_rcp_f32_e32 v46, v46
	v_rcp_f32_e32 v47, v47
	v_pk_mul_f32 v[56:57], v[56:57], v[50:51]
	v_cvt_pk_bf16_f32 v52, v54, v55
	v_add_co_u32_e32 v54, vcc, s4, v114
	s_mov_b64 s[10:11], 0x80000
	v_cvt_pk_bf16_f32 v50, v62, v63
	v_cvt_pk_bf16_f32 v51, v60, v61
	v_cvt_pk_bf16_f32 v53, v56, v57
	v_addc_co_u32_e32 v55, vcc, 0, v115, vcc
	v_lshl_add_u64 v[58:59], v[114:115], 0, s[10:11]
	global_store_dwordx4 v[54:55], v[50:53], off sc1
	v_pk_add_f32 v[42:43], v[42:43], 1.0 op_sel_hi:[1,0]
	v_mul_f32_e32 v38, 0xbfb8aa3b, v38
	v_cvt_pk_bf16_f32 v50, v66, v67
	v_cvt_pk_bf16_f32 v51, v68, v64
	v_cvt_pk_bf16_f32 v52, v65, v69
	v_cvt_pk_bf16_f32 v53, v70, v71
	global_store_dwordx4 v[58:59], v[50:53], off offset:2048 sc1
	v_pk_mul_f32 v[46:47], v[46:47], v[42:43]
	v_mul_f32_e32 v39, 0xbfb8aa3b, v39
	v_rcp_f32_e32 v50, v42
	v_mul_f32_e32 v42, 0xbfb8aa3b, v48
	v_exp_f32_e32 v42, v42
	v_exp_f32_e32 v38, v38
	v_exp_f32_e32 v39, v39
	v_max_f32_e32 v44, v44, v44
	v_add_f32_e32 v42, 1.0, v42
; __device__ __forceinline__ u32x4 pack8(const f32x4 a, const f32x4 b) { u32x4 w; w.x = cvt_pk_bf16(a[0], a[1]); w.y = cvt_pk_bf16(a[2], a[3]); w.z = cvt_pk_bf16(b[0], b[1]); w.w = cvt_pk_bf16(b[2], b[3]); return w; }
;     __device__ __forceinline__ void operator()(const f32x4 (&acc)[2][2][4][2], const Unit& u, int wr, int wc, int fr, int fq) const {
;     ...
;         if (pn >= 16) {
; #pragma unroll
;             for (int ai = 0; ai < 2; ++ai)
; #pragma unroll
;                 for (int m = 0; m < 4; ++m) { const int r = row0 + ai * HALF + m * 16;
;                     f32x4 ra[2], gb[2];
; #pragma unroll
;                     for (int n = 0; n < 2; ++n)
; #pragma unroll
;                         for (int i = 0; i < 4; ++i) { const float ea = __expf(-acc[ai][0][m][n][i]), eb = __expf(-fmaxf(acc[ai][1][m][n][i], -60.f));
;                             gb[n][i] = __builtin_amdgcn_rcpf(1.f + eb); ra[n][i] = (1.f + eb) * __builtin_amdgcn_rcpf(1.f + ea); }
;                     bf16_t* gp = gab + (size_t)r * 2048 + (pn - 16) * 128 + c8;
;                     *(u32x4*)gp = pack8(ra[0], ra[1]); *(u32x4*)(gp + 1024) = pack8(gb[0], gb[1]); }
	v_rcp_f32_e32 v48, v42
	v_mul_f32_e32 v42, 0xbfb8aa3b, v49
	v_exp_f32_e32 v42, v42
	v_max_f32_e32 v45, v45, v45
	v_max_f32_e32 v34, v34, v34
	v_max_f32_e32 v35, v35, v35
	v_max_f32_e32 v44, 0xc2700000, v44
	v_max_f32_e32 v45, 0xc2700000, v45
	v_max_f32_e32 v34, 0xc2700000, v34
	v_max_f32_e32 v35, 0xc2700000, v35
	v_mul_f32_e32 v44, 0xbfb8aa3b, v44
	v_mul_f32_e32 v45, 0xbfb8aa3b, v45
	v_mul_f32_e32 v34, 0xbfb8aa3b, v34
	v_mul_f32_e32 v35, 0xbfb8aa3b, v35
	v_exp_f32_e32 v44, v44
	v_exp_f32_e32 v45, v45
	v_add_f32_e32 v42, 1.0, v42
	v_exp_f32_e32 v34, v34
	v_add_f32_e32 v38, 1.0, v38
	v_exp_f32_e32 v35, v35
	v_add_f32_e32 v39, 1.0, v39
	v_rcp_f32_e32 v49, v42
	v_rcp_f32_e32 v38, v38
	v_rcp_f32_e32 v39, v39
	v_rcp_f32_e32 v51, v43
	v_pk_add_f32 v[42:43], v[44:45], 1.0 op_sel_hi:[1,0]
	v_pk_add_f32 v[34:35], v[34:35], 1.0 op_sel_hi:[1,0]
	v_pk_mul_f32 v[44:45], v[48:49], v[42:43]
	v_rcp_f32_e32 v49, v34
	v_pk_mul_f32 v[38:39], v[38:39], v[34:35]
	v_mul_f32_e32 v34, 0xbfb8aa3b, v40
	v_exp_f32_e32 v34, v34
	v_max_f32_e32 v36, v36, v36
	v_max_f32_e32 v37, v37, v37
	v_max_f32_e32 v36, 0xc2700000, v36
	v_add_f32_e32 v34, 1.0, v34
	v_rcp_f32_e32 v40, v34
	v_mul_f32_e32 v34, 0xbfb8aa3b, v41
	v_exp_f32_e32 v34, v34
	v_max_f32_e32 v37, 0xc2700000, v37
	v_mul_f32_e32 v36, 0xbfb8aa3b, v36
	v_mul_f32_e32 v37, 0xbfb8aa3b, v37
	v_exp_f32_e32 v36, v36
	v_exp_f32_e32 v37, v37
	v_mul_f32_e32 v30, 0xbfb8aa3b, v30
	v_mul_f32_e32 v31, 0xbfb8aa3b, v31
	v_exp_f32_e32 v30, v30
	v_exp_f32_e32 v31, v31
	v_add_f32_e32 v34, 1.0, v34
	v_max_f32_e32 v26, v26, v26
	v_max_f32_e32 v27, v27, v27
	v_rcp_f32_e32 v41, v34
	v_max_f32_e32 v26, 0xc2700000, v26
	v_max_f32_e32 v27, 0xc2700000, v27
	v_rcp_f32_e32 v53, v35
	v_pk_add_f32 v[34:35], v[36:37], 1.0 op_sel_hi:[1,0]
	v_mul_f32_e32 v26, 0xbfb8aa3b, v26
	v_mul_f32_e32 v27, 0xbfb8aa3b, v27
	v_rcp_f32_e32 v52, v42
	v_rcp_f32_e32 v48, v43
	v_rcp_f32_e32 v54, v34
	v_rcp_f32_e32 v55, v35
	v_exp_f32_e32 v26, v26
	v_add_f32_e32 v30, 1.0, v30
	v_exp_f32_e32 v27, v27
	v_add_f32_e32 v31, 1.0, v31
	s_mov_b32 s4, 0x90000
	v_rcp_f32_e32 v30, v30
	v_rcp_f32_e32 v31, v31
	v_pk_mul_f32 v[40:41], v[40:41], v[34:35]
	v_cvt_pk_bf16_f32 v36, v38, v39
	v_add_co_u32_e32 v38, vcc, s4, v114
	s_mov_b64 s[10:11], 0x90000
	v_cvt_pk_bf16_f32 v34, v46, v47
	v_cvt_pk_bf16_f32 v35, v44, v45
	v_cvt_pk_bf16_f32 v37, v40, v41
	v_addc_co_u32_e32 v39, vcc, 0, v115, vcc
	v_lshl_add_u64 v[42:43], v[114:115], 0, s[10:11]
	global_store_dwordx4 v[38:39], v[34:37], off sc1
	v_pk_add_f32 v[26:27], v[26:27], 1.0 op_sel_hi:[1,0]
	v_mul_f32_e32 v22, 0xbfb8aa3b, v22
	v_cvt_pk_bf16_f32 v34, v50, v51
	v_cvt_pk_bf16_f32 v35, v52, v48
	v_cvt_pk_bf16_f32 v36, v49, v53
	v_cvt_pk_bf16_f32 v37, v54, v55
	global_store_dwordx4 v[42:43], v[34:37], off offset:2048 sc1
	v_pk_mul_f32 v[30:31], v[30:31], v[26:27]
	v_mul_f32_e32 v23, 0xbfb8aa3b, v23
	v_rcp_f32_e32 v34, v26
	v_mul_f32_e32 v26, 0xbfb8aa3b, v32
	v_exp_f32_e32 v26, v26
	v_exp_f32_e32 v22, v22
	v_exp_f32_e32 v23, v23
	v_max_f32_e32 v28, v28, v28
	v_add_f32_e32 v26, 1.0, v26
	v_rcp_f32_e32 v32, v26
	v_mul_f32_e32 v26, 0xbfb8aa3b, v33
	v_exp_f32_e32 v26, v26
	v_max_f32_e32 v29, v29, v29
	v_max_f32_e32 v18, v18, v18
	v_max_f32_e32 v19, v19, v19
	v_max_f32_e32 v28, 0xc2700000, v28
	v_max_f32_e32 v29, 0xc2700000, v29
	v_max_f32_e32 v18, 0xc2700000, v18
	v_max_f32_e32 v19, 0xc2700000, v19
	v_mul_f32_e32 v28, 0xbfb8aa3b, v28
	v_mul_f32_e32 v29, 0xbfb8aa3b, v29
	v_mul_f32_e32 v18, 0xbfb8aa3b, v18
	v_mul_f32_e32 v19, 0xbfb8aa3b, v19
	v_exp_f32_e32 v28, v28
	v_exp_f32_e32 v29, v29
	v_add_f32_e32 v26, 1.0, v26
	v_exp_f32_e32 v18, v18
	v_add_f32_e32 v22, 1.0, v22
	v_exp_f32_e32 v19, v19
	v_add_f32_e32 v23, 1.0, v23
	v_rcp_f32_e32 v33, v26
	v_rcp_f32_e32 v22, v22
	v_rcp_f32_e32 v23, v23
	v_rcp_f32_e32 v35, v27
	v_pk_add_f32 v[26:27], v[28:29], 1.0 op_sel_hi:[1,0]
	v_pk_add_f32 v[18:19], v[18:19], 1.0 op_sel_hi:[1,0]
	v_pk_mul_f32 v[28:29], v[32:33], v[26:27]
	v_rcp_f32_e32 v33, v18
	v_pk_mul_f32 v[22:23], v[22:23], v[18:19]
	v_mul_f32_e32 v18, 0xbfb8aa3b, v24
	v_exp_f32_e32 v18, v18
	v_max_f32_e32 v20, v20, v20
	v_max_f32_e32 v21, v21, v21
	v_max_f32_e32 v20, 0xc2700000, v20
; __device__ __forceinline__ u32x4 pack8(const f32x4 a, const f32x4 b) { u32x4 w; w.x = cvt_pk_bf16(a[0], a[1]); w.y = cvt_pk_bf16(a[2], a[3]); w.z = cvt_pk_bf16(b[0], b[1]); w.w = cvt_pk_bf16(b[2], b[3]); return w; }
;     __device__ __forceinline__ void operator()(const f32x4 (&acc)[2][2][4][2], const Unit& u, int wr, int wc, int fr, int fq) const {
;     ...
;                 for (int m = 0; m < 4; ++m) { const int r = row0 + ai * HALF + m * 16;
;                     f32x4 ra[2], gb[2];
; #pragma unroll
;                     for (int n = 0; n < 2; ++n)
; #pragma unroll
;                         for (int i = 0; i < 4; ++i) { const float ea = __expf(-acc[ai][0][m][n][i]), eb = __expf(-fmaxf(acc[ai][1][m][n][i], -60.f));
;                             gb[n][i] = __builtin_amdgcn_rcpf(1.f + eb); ra[n][i] = (1.f + eb) * __builtin_amdgcn_rcpf(1.f + ea); }
;                     bf16_t* gp = gab + (size_t)r * 2048 + (pn - 16) * 128 + c8;
;                     *(u32x4*)gp = pack8(ra[0], ra[1]); *(u32x4*)(gp + 1024) = pack8(gb[0], gb[1]); }
	v_add_f32_e32 v18, 1.0, v18
	v_rcp_f32_e32 v24, v18
	v_mul_f32_e32 v18, 0xbfb8aa3b, v25
	v_exp_f32_e32 v18, v18
	v_max_f32_e32 v21, 0xc2700000, v21
	v_mul_f32_e32 v20, 0xbfb8aa3b, v20
	v_mul_f32_e32 v21, 0xbfb8aa3b, v21
	v_exp_f32_e32 v20, v20
	v_exp_f32_e32 v21, v21
	v_mul_f32_e32 v14, 0xbfb8aa3b, v14
	v_mul_f32_e32 v15, 0xbfb8aa3b, v15
	v_exp_f32_e32 v14, v14
	v_exp_f32_e32 v15, v15
	v_add_f32_e32 v18, 1.0, v18
	v_max_f32_e32 v10, v10, v10
	v_max_f32_e32 v11, v11, v11
	v_rcp_f32_e32 v25, v18
	v_max_f32_e32 v10, 0xc2700000, v10
	v_max_f32_e32 v11, 0xc2700000, v11
	v_rcp_f32_e32 v37, v19
	v_pk_add_f32 v[18:19], v[20:21], 1.0 op_sel_hi:[1,0]
	v_mul_f32_e32 v10, 0xbfb8aa3b, v10
	v_mul_f32_e32 v11, 0xbfb8aa3b, v11
	v_rcp_f32_e32 v36, v26
	v_rcp_f32_e32 v32, v27
	v_rcp_f32_e32 v38, v18
	v_rcp_f32_e32 v39, v19
	v_exp_f32_e32 v10, v10
	v_add_f32_e32 v14, 1.0, v14
	v_exp_f32_e32 v11, v11
	v_add_f32_e32 v15, 1.0, v15
	s_mov_b32 s4, 0xa0000
	v_rcp_f32_e32 v14, v14
	v_rcp_f32_e32 v15, v15
	v_pk_mul_f32 v[24:25], v[24:25], v[18:19]
	v_cvt_pk_bf16_f32 v20, v22, v23
	v_add_co_u32_e32 v22, vcc, s4, v114
	s_mov_b64 s[10:11], 0xa0000
	v_cvt_pk_bf16_f32 v18, v30, v31
	v_cvt_pk_bf16_f32 v19, v28, v29
	v_cvt_pk_bf16_f32 v21, v24, v25
	v_addc_co_u32_e32 v23, vcc, 0, v115, vcc
	v_lshl_add_u64 v[26:27], v[114:115], 0, s[10:11]
	global_store_dwordx4 v[22:23], v[18:21], off sc1
	v_pk_add_f32 v[10:11], v[10:11], 1.0 op_sel_hi:[1,0]
	v_mul_f32_e32 v6, 0xbfb8aa3b, v6
	v_cvt_pk_bf16_f32 v18, v34, v35
	v_cvt_pk_bf16_f32 v19, v36, v32
	v_cvt_pk_bf16_f32 v20, v33, v37
	v_cvt_pk_bf16_f32 v21, v38, v39
	global_store_dwordx4 v[26:27], v[18:21], off offset:2048 sc1
	v_pk_mul_f32 v[14:15], v[14:15], v[10:11]
	v_mul_f32_e32 v7, 0xbfb8aa3b, v7
	v_rcp_f32_e32 v18, v10
	v_mul_f32_e32 v10, 0xbfb8aa3b, v16
	v_exp_f32_e32 v10, v10
	v_exp_f32_e32 v6, v6
	v_exp_f32_e32 v7, v7
	v_max_f32_e32 v12, v12, v12
	v_add_f32_e32 v10, 1.0, v10
	v_rcp_f32_e32 v16, v10
	v_mul_f32_e32 v10, 0xbfb8aa3b, v17
	v_exp_f32_e32 v10, v10
	v_max_f32_e32 v13, v13, v13
	v_max_f32_e32 v2, v2, v2
	v_max_f32_e32 v3, v3, v3
	v_max_f32_e32 v12, 0xc2700000, v12
	v_max_f32_e32 v13, 0xc2700000, v13
	v_max_f32_e32 v2, 0xc2700000, v2
	v_max_f32_e32 v3, 0xc2700000, v3
	v_mul_f32_e32 v12, 0xbfb8aa3b, v12
	v_mul_f32_e32 v13, 0xbfb8aa3b, v13
	v_mul_f32_e32 v2, 0xbfb8aa3b, v2
	v_mul_f32_e32 v3, 0xbfb8aa3b, v3
	v_exp_f32_e32 v12, v12
	v_exp_f32_e32 v13, v13
	v_add_f32_e32 v10, 1.0, v10
	v_exp_f32_e32 v2, v2
	v_add_f32_e32 v6, 1.0, v6
	v_exp_f32_e32 v3, v3
	v_add_f32_e32 v7, 1.0, v7
	v_rcp_f32_e32 v17, v10
	v_rcp_f32_e32 v6, v6
	v_rcp_f32_e32 v7, v7
	v_rcp_f32_e32 v19, v11
	v_pk_add_f32 v[10:11], v[12:13], 1.0 op_sel_hi:[1,0]
	v_pk_add_f32 v[2:3], v[2:3], 1.0 op_sel_hi:[1,0]
	v_pk_mul_f32 v[12:13], v[16:17], v[10:11]
	v_rcp_f32_e32 v17, v2
	v_pk_mul_f32 v[6:7], v[6:7], v[2:3]
	v_mul_f32_e32 v2, 0xbfb8aa3b, v8
	v_exp_f32_e32 v2, v2
	v_max_f32_e32 v4, v4, v4
	v_max_f32_e32 v5, v5, v5
	v_max_f32_e32 v4, 0xc2700000, v4
	v_add_f32_e32 v2, 1.0, v2
	v_rcp_f32_e32 v8, v2
	v_mul_f32_e32 v2, 0xbfb8aa3b, v9
	v_exp_f32_e32 v2, v2
	v_max_f32_e32 v5, 0xc2700000, v5
	v_mul_f32_e32 v4, 0xbfb8aa3b, v4
	v_mul_f32_e32 v5, 0xbfb8aa3b, v5
	v_exp_f32_e32 v4, v4
	v_exp_f32_e32 v5, v5
	v_add_f32_e32 v2, 1.0, v2
	v_rcp_f32_e32 v9, v2
	v_rcp_f32_e32 v21, v3
	v_pk_add_f32 v[2:3], v[4:5], 1.0 op_sel_hi:[1,0]
	v_rcp_f32_e32 v20, v10
	v_rcp_f32_e32 v16, v11
	v_rcp_f32_e32 v22, v2
	v_rcp_f32_e32 v23, v3
	s_mov_b32 s4, 0xb0000
	v_pk_mul_f32 v[8:9], v[8:9], v[2:3]
	v_cvt_pk_bf16_f32 v4, v6, v7
	v_add_co_u32_e32 v6, vcc, s4, v114
	s_mov_b64 s[10:11], 0xb0000
	v_cvt_pk_bf16_f32 v2, v14, v15
	v_cvt_pk_bf16_f32 v3, v12, v13
	v_cvt_pk_bf16_f32 v5, v8, v9
	v_addc_co_u32_e32 v7, vcc, 0, v115, vcc
	v_lshl_add_u64 v[10:11], v[114:115], 0, s[10:11]
	global_store_dwordx4 v[6:7], v[2:5], off sc1
	s_nop 1
	v_cvt_pk_bf16_f32 v2, v18, v19
	v_cvt_pk_bf16_f32 v3, v20, v16
	v_cvt_pk_bf16_f32 v4, v17, v21
	v_cvt_pk_bf16_f32 v5, v22, v23
	global_store_dwordx4 v[10:11], v[2:5], off offset:2048 sc1
	s_andn2_b64 vcc, exec, s[8:9]
	s_mov_b64 s[8:9], -1
	s_cbranch_vccnz .LBB0_131
	s_branch .LBB0_259

; __host__ __device__ __forceinline__ void tile_hp(int q, int bj, int& h, int& part) { if (q < 4) { h = q; part = bj; } else if (q < 6) { h = 2 * (q - 4) + bj; part = 2; } else { h = 2 * (q - 6) + bj; part = 3; } }
; __device__ __forceinline__ float sigmoidf_(float x) { return __builtin_amdgcn_rcpf(1.f + __expf(-x)); }
; __device__ __forceinline__ float siluf_(float x) { return x * __builtin_amdgcn_rcpf(1.f + __expf(-x)); }
;     __device__ __forceinline__ void operator()(const f32x4 (&acc)[2][2][4][2], const Unit& u, int wr, int wc, int fr, int fq) const {
;     ...
;         bf16_t* base = grp ? dnr : hgr;
; #pragma unroll
;         for (int bj = 0; bj < 2; ++bj) {
;             int h, part; tile_hp(q, bj, h, part);
;             const int mode = (part == 3) ? 3 : (grp == 0 ? (part == 0 ? 1 : (part == 1 ? 2 : 0)) : 0);
;             float lb[8];
; #pragma unroll
;             for (int i = 0; i < 8; ++i) lb[i] = 0.f;
;             if (mode == 2) {
; #pragma unroll
;                 for (int i = 0; i < 8; ++i) { const int ch = h * 128 + c8 + i; lb[i] = sigmoidf_(lbl[ch] - lbl[512 + ch]); }
;             }
; #pragma unroll
;             for (int ai = 0; ai < 2; ++ai)
; #pragma unroll
;                 for (int m = 0; m < 4; ++m) { const int r = row0 + ai * HALF + m * 16;
;                     f32x4 v0 = acc[ai][bj][m][0], v1 = acc[ai][bj][m][1];
;                     if (mode == 1) {
; #pragma unroll
;                         for (int i = 0; i < 4; ++i) { v0[i] = siluf_(v0[i]) * QSCALE; v1[i] = siluf_(v1[i]) * QSCALE; }
;                     } else if (mode == 2) {
; #pragma unroll
;                         for (int i = 0; i < 4; ++i) { v0[i] = __logf(lb[i] + (1.f - lb[i]) * sigmoidf_(v0[i])); v1[i] = __logf(lb[4 + i] + (1.f - lb[4 + i]) * sigmoidf_(v1[i])); }
;                     } else if (mode == 3) {
; #pragma unroll
;                         for (int i = 0; i < 4; ++i) { v0[i] = siluf_(v0[i]); v1[i] = siluf_(v1[i]); }
;                     }
;                     const u32x4 w = pack8(v0, v1);
;                     *(u32x4*)(base + ((size_t)((r >> 6) * 4 + h)) * 32768 + part * 8192 + (r & 63) * 128 + c8) = w;
;                     if (grp == 1 && part < 3 && m == 3 && fr >= 13) *(u32x4*)(halo + (size_t)(r >> 6) * 4608 + (fr - 13) * 1536 + h * 384 + part * 128 + c8) = w;
.LBB0_150:
	s_and_b64 s[12:13], s[72:73], exec
	s_cselect_b32 s13, s27, s63
	s_cselect_b32 s12, s26, s62
	v_lshlrev_b32_e32 v146, 1, v158
	s_ashr_i32 s33, s49, 4
	v_lshl_add_u64 v[178:179], s[12:13], 0, v[146:147]
	s_add_i32 s12, s37, s33
	s_lshl_b32 s38, s4, 14
	s_ashr_i32 s13, s12, 31
	v_lshl_add_u64 v[180:181], v[178:179], 0, s[38:39]
	s_lshl_b64 s[12:13], s[12:13], 16
	v_lshl_add_u64 v[176:177], v[180:181], 0, s[12:13]
	v_lshlrev_b32_e32 v174, 1, v148
	v_mov_b32_e32 v175, v147
	v_cvt_pk_bf16_f32 v130, v130, v131
	v_cvt_pk_bf16_f32 v131, v132, v133
	v_cvt_pk_bf16_f32 v132, v134, v135
	v_cvt_pk_bf16_f32 v133, v136, v137
	v_lshl_add_u64 v[134:135], v[176:177], 0, v[174:175]
	global_store_dwordx4 v[134:135], v[130:133], off sc1
	s_andn2_b64 vcc, exec, s[16:17]
	s_nop 0
	v_cndmask_b32_e64 v130, 0, 1, s[16:17]
	v_cmp_ne_u32_e64 s[12:13], 1, v130
	s_mov_b64 s[16:17], -1
	s_cbranch_vccnz .LBB0_154
	v_mov_b64_e32 v[136:137], v[104:105]
	v_mov_b64_e32 v[132:133], v[112:113]
	s_and_b64 vcc, exec, s[10:11]
	v_mov_b64_e32 v[134:135], v[102:103]
	v_mov_b64_e32 v[130:131], v[110:111]
	s_cbranch_vccnz .LBB0_153
	v_mul_f32_e32 v131, 0xbfb8aa3b, v102
	v_mul_f32_e32 v132, 0xbfb8aa3b, v111
	v_exp_f32_e32 v131, v131
	v_exp_f32_e32 v132, v132
	v_mul_f32_e32 v133, 0xbfb8aa3b, v112
	v_mul_f32_e32 v135, 0xbfb8aa3b, v104
	v_add_f32_e32 v131, 1.0, v131
	v_rcp_f32_e32 v134, v131
	v_add_f32_e32 v131, 1.0, v132
	v_mul_f32_e32 v132, 0xbfb8aa3b, v103
	v_exp_f32_e32 v132, v132
	v_exp_f32_e32 v133, v133
	v_exp_f32_e32 v135, v135
	v_mul_f32_e32 v130, 0xbfb8aa3b, v110
	v_add_f32_e32 v168, 1.0, v132
	v_add_f32_e32 v132, 1.0, v133
	v_add_f32_e32 v133, 1.0, v135
	v_mul_f32_e32 v135, 0xbfb8aa3b, v113
	v_mul_f32_e32 v136, 0xbfb8aa3b, v105
	v_exp_f32_e32 v130, v130
	v_exp_f32_e32 v135, v135
	v_exp_f32_e32 v137, v136
	v_rcp_f32_e32 v136, v133
	v_add_f32_e32 v130, 1.0, v130
	v_add_f32_e32 v133, 1.0, v135
	v_add_f32_e32 v135, 1.0, v137
	v_rcp_f32_e32 v130, v130
	v_rcp_f32_e32 v131, v131
	v_rcp_f32_e32 v132, v132
	v_rcp_f32_e32 v133, v133
	v_rcp_f32_e32 v137, v135
	v_rcp_f32_e32 v135, v168
	v_pk_mul_f32 v[130:131], v[110:111], v[130:131]
	v_pk_mul_f32 v[132:133], v[112:113], v[132:133]
	v_pk_mul_f32 v[136:137], v[104:105], v[136:137]
	v_pk_mul_f32 v[134:135], v[102:103], v[134:135]

; __device__ __forceinline__ float sigmoidf_(float x) { return __builtin_amdgcn_rcpf(1.f + __expf(-x)); }
; __device__ __forceinline__ float siluf_(float x) { return x * __builtin_amdgcn_rcpf(1.f + __expf(-x)); }
; __device__ __forceinline__ u32x4 pack8(const f32x4 a, const f32x4 b) { u32x4 w; w.x = cvt_pk_bf16(a[0], a[1]); w.y = cvt_pk_bf16(a[2], a[3]); w.z = cvt_pk_bf16(b[0], b[1]); w.w = cvt_pk_bf16(b[2], b[3]); return w; }
;     __device__ __forceinline__ void operator()(const f32x4 (&acc)[2][2][4][2], const Unit& u, int wr, int wc, int fr, int fq) const {
;     ...
;                 for (int m = 0; m < 4; ++m) { const int r = row0 + ai * HALF + m * 16;
;                     f32x4 v0 = acc[ai][bj][m][0], v1 = acc[ai][bj][m][1];
;                     if (mode == 1) {
; #pragma unroll
;                         for (int i = 0; i < 4; ++i) { v0[i] = siluf_(v0[i]) * QSCALE; v1[i] = siluf_(v1[i]) * QSCALE; }
;                     } else if (mode == 2) {
; #pragma unroll
;                         for (int i = 0; i < 4; ++i) { v0[i] = __logf(lb[i] + (1.f - lb[i]) * sigmoidf_(v0[i])); v1[i] = __logf(lb[4 + i] + (1.f - lb[4 + i]) * sigmoidf_(v1[i])); }
;                     } else if (mode == 3) {
; #pragma unroll
;                         for (int i = 0; i < 4; ++i) { v0[i] = siluf_(v0[i]); v1[i] = siluf_(v1[i]); }
;                     }
;                     const u32x4 w = pack8(v0, v1);
;                     *(u32x4*)(base + ((size_t)((r >> 6) * 4 + h)) * 32768 + part * 8192 + (r & 63) * 128 + c8) = w;
;                     if (grp == 1 && part < 3 && m == 3 && fr >= 13) *(u32x4*)(halo + (size_t)(r >> 6) * 4608 + (fr - 13) * 1536 + h * 384 + part * 128 + c8) = w;
.LBB0_156:
	v_lshlrev_b32_e32 v172, 1, v150
	v_mov_b32_e32 v173, v147
	v_cvt_pk_bf16_f32 v130, v130, v131
	v_cvt_pk_bf16_f32 v131, v132, v133
	v_cvt_pk_bf16_f32 v132, v134, v135
	v_cvt_pk_bf16_f32 v133, v136, v137
	v_lshl_add_u64 v[134:135], v[176:177], 0, v[172:173]
	s_and_b64 vcc, exec, s[12:13]
	s_mov_b64 s[16:17], -1
	global_store_dwordx4 v[134:135], v[130:133], off sc1
	s_cbranch_vccnz .LBB0_160
	v_mov_b64_e32 v[136:137], v[88:89]
	v_mov_b64_e32 v[132:133], v[96:97]
	s_and_b64 vcc, exec, s[10:11]
	v_mov_b64_e32 v[134:135], v[86:87]
	v_mov_b64_e32 v[130:131], v[94:95]
	s_cbranch_vccnz .LBB0_159
	v_mul_f32_e32 v131, 0xbfb8aa3b, v86
	v_mul_f32_e32 v132, 0xbfb8aa3b, v95
	v_exp_f32_e32 v131, v131
	v_exp_f32_e32 v132, v132
	v_mul_f32_e32 v133, 0xbfb8aa3b, v96
	v_mul_f32_e32 v135, 0xbfb8aa3b, v88
	v_add_f32_e32 v131, 1.0, v131
	v_rcp_f32_e32 v134, v131
	v_add_f32_e32 v131, 1.0, v132
	v_mul_f32_e32 v132, 0xbfb8aa3b, v87
	v_exp_f32_e32 v132, v132
	v_exp_f32_e32 v133, v133
	v_exp_f32_e32 v135, v135
	v_mul_f32_e32 v130, 0xbfb8aa3b, v94
	v_add_f32_e32 v168, 1.0, v132
	v_add_f32_e32 v132, 1.0, v133
	v_add_f32_e32 v133, 1.0, v135
	v_mul_f32_e32 v135, 0xbfb8aa3b, v97
	v_mul_f32_e32 v136, 0xbfb8aa3b, v89
	v_exp_f32_e32 v130, v130
	v_exp_f32_e32 v135, v135
	v_exp_f32_e32 v137, v136
	v_rcp_f32_e32 v136, v133
	v_add_f32_e32 v130, 1.0, v130
	v_add_f32_e32 v133, 1.0, v135
	v_add_f32_e32 v135, 1.0, v137
	v_rcp_f32_e32 v130, v130
	v_rcp_f32_e32 v131, v131
	v_rcp_f32_e32 v132, v132
	v_rcp_f32_e32 v133, v133
	v_rcp_f32_e32 v137, v135
	v_rcp_f32_e32 v135, v168
	v_pk_mul_f32 v[130:131], v[94:95], v[130:131]
	v_pk_mul_f32 v[132:133], v[96:97], v[132:133]
	v_pk_mul_f32 v[136:137], v[88:89], v[136:137]
	v_pk_mul_f32 v[134:135], v[86:87], v[134:135]

; __device__ __forceinline__ float sigmoidf_(float x) { return __builtin_amdgcn_rcpf(1.f + __expf(-x)); }
; __device__ __forceinline__ float siluf_(float x) { return x * __builtin_amdgcn_rcpf(1.f + __expf(-x)); }
; __device__ __forceinline__ u32x4 pack8(const f32x4 a, const f32x4 b) { u32x4 w; w.x = cvt_pk_bf16(a[0], a[1]); w.y = cvt_pk_bf16(a[2], a[3]); w.z = cvt_pk_bf16(b[0], b[1]); w.w = cvt_pk_bf16(b[2], b[3]); return w; }
;     __device__ __forceinline__ void operator()(const f32x4 (&acc)[2][2][4][2], const Unit& u, int wr, int wc, int fr, int fq) const {
;     ...
;                 for (int m = 0; m < 4; ++m) { const int r = row0 + ai * HALF + m * 16;
;                     f32x4 v0 = acc[ai][bj][m][0], v1 = acc[ai][bj][m][1];
;                     if (mode == 1) {
; #pragma unroll
;                         for (int i = 0; i < 4; ++i) { v0[i] = siluf_(v0[i]) * QSCALE; v1[i] = siluf_(v1[i]) * QSCALE; }
;                     } else if (mode == 2) {
; #pragma unroll
;                         for (int i = 0; i < 4; ++i) { v0[i] = __logf(lb[i] + (1.f - lb[i]) * sigmoidf_(v0[i])); v1[i] = __logf(lb[4 + i] + (1.f - lb[4 + i]) * sigmoidf_(v1[i])); }
;                     } else if (mode == 3) {
; #pragma unroll
;                         for (int i = 0; i < 4; ++i) { v0[i] = siluf_(v0[i]); v1[i] = siluf_(v1[i]); }
;                     }
;                     const u32x4 w = pack8(v0, v1);
;                     *(u32x4*)(base + ((size_t)((r >> 6) * 4 + h)) * 32768 + part * 8192 + (r & 63) * 128 + c8) = w;
;                     if (grp == 1 && part < 3 && m == 3 && fr >= 13) *(u32x4*)(halo + (size_t)(r >> 6) * 4608 + (fr - 13) * 1536 + h * 384 + part * 128 + c8) = w;
.LBB0_162:
	v_lshlrev_b32_e32 v170, 1, v152
	v_mov_b32_e32 v171, v147
	v_cvt_pk_bf16_f32 v130, v130, v131
	v_cvt_pk_bf16_f32 v131, v132, v133
	v_cvt_pk_bf16_f32 v132, v134, v135
	v_cvt_pk_bf16_f32 v133, v136, v137
	v_lshl_add_u64 v[134:135], v[176:177], 0, v[170:171]
	s_and_b64 vcc, exec, s[12:13]
	s_mov_b64 s[16:17], -1
	global_store_dwordx4 v[134:135], v[130:133], off sc1
	s_cbranch_vccnz .LBB0_166
	v_mov_b64_e32 v[136:137], v[72:73]
	v_mov_b64_e32 v[132:133], v[80:81]
	s_and_b64 vcc, exec, s[10:11]
	v_mov_b64_e32 v[134:135], v[70:71]
	v_mov_b64_e32 v[130:131], v[78:79]
	s_cbranch_vccnz .LBB0_165
	v_mul_f32_e32 v131, 0xbfb8aa3b, v70
	v_mul_f32_e32 v132, 0xbfb8aa3b, v79
	v_exp_f32_e32 v131, v131
	v_exp_f32_e32 v132, v132
	v_mul_f32_e32 v133, 0xbfb8aa3b, v80
	v_mul_f32_e32 v135, 0xbfb8aa3b, v72
	v_add_f32_e32 v131, 1.0, v131
	v_rcp_f32_e32 v134, v131
	v_add_f32_e32 v131, 1.0, v132
	v_mul_f32_e32 v132, 0xbfb8aa3b, v71
	v_exp_f32_e32 v132, v132
	v_exp_f32_e32 v133, v133
	v_exp_f32_e32 v135, v135
	v_mul_f32_e32 v130, 0xbfb8aa3b, v78
	v_add_f32_e32 v168, 1.0, v132
	v_add_f32_e32 v132, 1.0, v133
	v_add_f32_e32 v133, 1.0, v135
	v_mul_f32_e32 v135, 0xbfb8aa3b, v81
	v_mul_f32_e32 v136, 0xbfb8aa3b, v73
	v_exp_f32_e32 v130, v130
	v_exp_f32_e32 v135, v135
	v_exp_f32_e32 v137, v136
	v_rcp_f32_e32 v136, v133
	v_add_f32_e32 v130, 1.0, v130
	v_add_f32_e32 v133, 1.0, v135
	v_add_f32_e32 v135, 1.0, v137
	v_rcp_f32_e32 v130, v130
	v_rcp_f32_e32 v131, v131
	v_rcp_f32_e32 v132, v132
	v_rcp_f32_e32 v133, v133
	v_rcp_f32_e32 v137, v135
	v_rcp_f32_e32 v135, v168
	v_pk_mul_f32 v[130:131], v[78:79], v[130:131]
	v_pk_mul_f32 v[132:133], v[80:81], v[132:133]
	v_pk_mul_f32 v[136:137], v[72:73], v[136:137]
	v_pk_mul_f32 v[134:135], v[70:71], v[134:135]

; __device__ __forceinline__ u32x4 pack8(const f32x4 a, const f32x4 b) { u32x4 w; w.x = cvt_pk_bf16(a[0], a[1]); w.y = cvt_pk_bf16(a[2], a[3]); w.z = cvt_pk_bf16(b[0], b[1]); w.w = cvt_pk_bf16(b[2], b[3]); return w; }
;     __device__ __forceinline__ void operator()(const f32x4 (&acc)[2][2][4][2], const Unit& u, int wr, int wc, int fr, int fq) const {
;     ...
;                     const u32x4 w = pack8(v0, v1);
;                     *(u32x4*)(base + ((size_t)((r >> 6) * 4 + h)) * 32768 + part * 8192 + (r & 63) * 128 + c8) = w;
;                     if (grp == 1 && part < 3 && m == 3 && fr >= 13) *(u32x4*)(halo + (size_t)(r >> 6) * 4608 + (fr - 13) * 1536 + h * 384 + part * 128 + c8) = w;
.LBB0_168:
	s_cmp_gt_i32 s96, 7
	s_cselect_b64 s[16:17], -1, 0
	s_ashr_i32 s38, s49, 6
	s_and_b64 s[78:79], s[16:17], s[76:77]
	s_mul_i32 s76, s37, 0x180
	s_mul_hi_i32 s81, s38, 0x2400
	s_mul_i32 s80, s38, 0x2400
	v_lshlrev_b32_e32 v168, 1, v154
	v_mov_b32_e32 v169, v147
	s_ashr_i32 s77, s76, 31
	s_lshl_b32 s4, s4, 7
	v_cvt_pk_bf16_f32 v130, v130, v131
	v_cvt_pk_bf16_f32 v131, v132, v133
	v_cvt_pk_bf16_f32 v132, v134, v135
	v_cvt_pk_bf16_f32 v133, v136, v137
	v_lshl_add_u64 v[134:135], v[176:177], 0, v[168:169]
	s_and_b64 s[78:79], s[78:79], s[6:7]
	v_lshl_add_u64 v[176:177], v[156:157], 0, s[80:81]
	global_store_dwordx4 v[134:135], v[130:133], off sc1
	s_and_saveexec_b64 s[80:81], s[78:79]
	s_cbranch_execz .LBB0_170
	v_lshl_add_u64 v[134:135], s[76:77], 1, v[176:177]
	s_lshl_b32 s38, s4, 1
	v_lshl_add_u64 v[134:135], v[134:135], 0, s[38:39]
	v_lshl_add_u64 v[134:135], v[134:135], 0, v[146:147]
	v_add_co_u32_e32 v134, vcc, 0xffff7000, v134
	s_nop 1
	v_addc_co_u32_e32 v135, vcc, -1, v135, vcc
	global_store_dwordx4 v[134:135], v[130:133], off offset:-3072 sc1

; __device__ __forceinline__ float sigmoidf_(float x) { return __builtin_amdgcn_rcpf(1.f + __expf(-x)); }
; __device__ __forceinline__ float siluf_(float x) { return x * __builtin_amdgcn_rcpf(1.f + __expf(-x)); }
; __device__ __forceinline__ u32x4 pack8(const f32x4 a, const f32x4 b) { u32x4 w; w.x = cvt_pk_bf16(a[0], a[1]); w.y = cvt_pk_bf16(a[2], a[3]); w.z = cvt_pk_bf16(b[0], b[1]); w.w = cvt_pk_bf16(b[2], b[3]); return w; }
;     __device__ __forceinline__ void operator()(const f32x4 (&acc)[2][2][4][2], const Unit& u, int wr, int wc, int fr, int fq) const {
;     ...
;                 for (int m = 0; m < 4; ++m) { const int r = row0 + ai * HALF + m * 16;
;                     f32x4 v0 = acc[ai][bj][m][0], v1 = acc[ai][bj][m][1];
;                     if (mode == 1) {
; #pragma unroll
;                         for (int i = 0; i < 4; ++i) { v0[i] = siluf_(v0[i]) * QSCALE; v1[i] = siluf_(v1[i]) * QSCALE; }
;                     } else if (mode == 2) {
; #pragma unroll
;                         for (int i = 0; i < 4; ++i) { v0[i] = __logf(lb[i] + (1.f - lb[i]) * sigmoidf_(v0[i])); v1[i] = __logf(lb[4 + i] + (1.f - lb[4 + i]) * sigmoidf_(v1[i])); }
;                     } else if (mode == 3) {
; #pragma unroll
;                         for (int i = 0; i < 4; ++i) { v0[i] = siluf_(v0[i]); v1[i] = siluf_(v1[i]); }
;                     }
;                     const u32x4 w = pack8(v0, v1);
;                     *(u32x4*)(base + ((size_t)((r >> 6) * 4 + h)) * 32768 + part * 8192 + (r & 63) * 128 + c8) = w;
;                     if (grp == 1 && part < 3 && m == 3 && fr >= 13) *(u32x4*)(halo + (size_t)(r >> 6) * 4608 + (fr - 13) * 1536 + h * 384 + part * 128 + c8) = w;
.LBB0_176:
	s_add_i32 s38, s49, 0x80
	s_ashr_i32 s97, s38, 4
	s_add_i32 s80, s37, s97
	s_ashr_i32 s81, s80, 31
	s_lshl_b64 s[80:81], s[80:81], 16
	v_lshl_add_u64 v[180:181], v[180:181], 0, s[80:81]
	v_mov_b32_e32 v175, v147
	v_cvt_pk_bf16_f32 v130, v130, v131
	v_cvt_pk_bf16_f32 v131, v132, v133
	v_cvt_pk_bf16_f32 v132, v134, v135
	v_cvt_pk_bf16_f32 v133, v136, v137
	v_lshl_add_u64 v[134:135], v[180:181], 0, v[174:175]
	s_and_b64 vcc, exec, s[12:13]
	s_mov_b64 s[80:81], -1
	global_store_dwordx4 v[134:135], v[130:133], off sc1
	s_cbranch_vccnz .LBB0_180
	v_mov_b64_e32 v[136:137], v[40:41]
	v_mov_b64_e32 v[132:133], v[48:49]
	s_and_b64 vcc, exec, s[10:11]
	v_mov_b64_e32 v[134:135], v[38:39]
	v_mov_b64_e32 v[130:131], v[46:47]
	s_cbranch_vccnz .LBB0_179
	v_mul_f32_e32 v131, 0xbfb8aa3b, v38
	v_mul_f32_e32 v132, 0xbfb8aa3b, v47
	v_exp_f32_e32 v131, v131
	v_exp_f32_e32 v132, v132
	v_mul_f32_e32 v133, 0xbfb8aa3b, v48
	v_mul_f32_e32 v135, 0xbfb8aa3b, v40
	v_add_f32_e32 v131, 1.0, v131
	v_rcp_f32_e32 v134, v131
	v_add_f32_e32 v131, 1.0, v132
	v_mul_f32_e32 v132, 0xbfb8aa3b, v39
	v_exp_f32_e32 v132, v132
	v_exp_f32_e32 v133, v133
	v_exp_f32_e32 v135, v135
	v_mul_f32_e32 v130, 0xbfb8aa3b, v46
	v_add_f32_e32 v169, 1.0, v132
	v_add_f32_e32 v132, 1.0, v133
	v_add_f32_e32 v133, 1.0, v135
	v_mul_f32_e32 v135, 0xbfb8aa3b, v49
	v_mul_f32_e32 v136, 0xbfb8aa3b, v41
	v_exp_f32_e32 v130, v130
	v_exp_f32_e32 v135, v135
	v_exp_f32_e32 v137, v136
	v_rcp_f32_e32 v136, v133
	v_add_f32_e32 v130, 1.0, v130
	v_add_f32_e32 v133, 1.0, v135
	v_add_f32_e32 v135, 1.0, v137
	v_rcp_f32_e32 v130, v130
	v_rcp_f32_e32 v131, v131
	v_rcp_f32_e32 v132, v132
	v_rcp_f32_e32 v133, v133
	v_rcp_f32_e32 v137, v135
	v_rcp_f32_e32 v135, v169
	v_pk_mul_f32 v[130:131], v[46:47], v[130:131]
	v_pk_mul_f32 v[132:133], v[48:49], v[132:133]
	v_pk_mul_f32 v[136:137], v[40:41], v[136:137]
	v_pk_mul_f32 v[134:135], v[38:39], v[134:135]

; __device__ __forceinline__ float sigmoidf_(float x) { return __builtin_amdgcn_rcpf(1.f + __expf(-x)); }
; __device__ __forceinline__ float siluf_(float x) { return x * __builtin_amdgcn_rcpf(1.f + __expf(-x)); }
; __device__ __forceinline__ u32x4 pack8(const f32x4 a, const f32x4 b) { u32x4 w; w.x = cvt_pk_bf16(a[0], a[1]); w.y = cvt_pk_bf16(a[2], a[3]); w.z = cvt_pk_bf16(b[0], b[1]); w.w = cvt_pk_bf16(b[2], b[3]); return w; }
;     __device__ __forceinline__ void operator()(const f32x4 (&acc)[2][2][4][2], const Unit& u, int wr, int wc, int fr, int fq) const {
;     ...
;                 for (int m = 0; m < 4; ++m) { const int r = row0 + ai * HALF + m * 16;
;                     f32x4 v0 = acc[ai][bj][m][0], v1 = acc[ai][bj][m][1];
;                     if (mode == 1) {
; #pragma unroll
;                         for (int i = 0; i < 4; ++i) { v0[i] = siluf_(v0[i]) * QSCALE; v1[i] = siluf_(v1[i]) * QSCALE; }
;                     } else if (mode == 2) {
; #pragma unroll
;                         for (int i = 0; i < 4; ++i) { v0[i] = __logf(lb[i] + (1.f - lb[i]) * sigmoidf_(v0[i])); v1[i] = __logf(lb[4 + i] + (1.f - lb[4 + i]) * sigmoidf_(v1[i])); }
;                     } else if (mode == 3) {
; #pragma unroll
;                         for (int i = 0; i < 4; ++i) { v0[i] = siluf_(v0[i]); v1[i] = siluf_(v1[i]); }
;                     }
;                     const u32x4 w = pack8(v0, v1);
;                     *(u32x4*)(base + ((size_t)((r >> 6) * 4 + h)) * 32768 + part * 8192 + (r & 63) * 128 + c8) = w;
;                     if (grp == 1 && part < 3 && m == 3 && fr >= 13) *(u32x4*)(halo + (size_t)(r >> 6) * 4608 + (fr - 13) * 1536 + h * 384 + part * 128 + c8) = w;
.LBB0_182:
	v_mov_b32_e32 v173, v147
	v_cvt_pk_bf16_f32 v130, v130, v131
	v_cvt_pk_bf16_f32 v131, v132, v133
	v_cvt_pk_bf16_f32 v132, v134, v135
	v_cvt_pk_bf16_f32 v133, v136, v137
	v_lshl_add_u64 v[134:135], v[180:181], 0, v[172:173]
	s_and_b64 vcc, exec, s[12:13]
	s_mov_b64 s[80:81], -1
	global_store_dwordx4 v[134:135], v[130:133], off sc1
	s_cbranch_vccnz .LBB0_186
	v_mov_b64_e32 v[136:137], v[24:25]
	v_mov_b64_e32 v[132:133], v[32:33]
	s_and_b64 vcc, exec, s[10:11]
	v_mov_b64_e32 v[134:135], v[22:23]
	v_mov_b64_e32 v[130:131], v[30:31]
	s_cbranch_vccnz .LBB0_185
	v_mul_f32_e32 v131, 0xbfb8aa3b, v22
	v_mul_f32_e32 v132, 0xbfb8aa3b, v31
	v_exp_f32_e32 v131, v131
	v_exp_f32_e32 v132, v132
	v_mul_f32_e32 v133, 0xbfb8aa3b, v32
	v_mul_f32_e32 v135, 0xbfb8aa3b, v24
	v_add_f32_e32 v131, 1.0, v131
	v_rcp_f32_e32 v134, v131
	v_add_f32_e32 v131, 1.0, v132
	v_mul_f32_e32 v132, 0xbfb8aa3b, v23
	v_exp_f32_e32 v132, v132
	v_exp_f32_e32 v133, v133
	v_exp_f32_e32 v135, v135
	v_mul_f32_e32 v130, 0xbfb8aa3b, v30
	v_add_f32_e32 v169, 1.0, v132
	v_add_f32_e32 v132, 1.0, v133
	v_add_f32_e32 v133, 1.0, v135
	v_mul_f32_e32 v135, 0xbfb8aa3b, v33
	v_mul_f32_e32 v136, 0xbfb8aa3b, v25
	v_exp_f32_e32 v130, v130
	v_exp_f32_e32 v135, v135
	v_exp_f32_e32 v137, v136
	v_rcp_f32_e32 v136, v133
	v_add_f32_e32 v130, 1.0, v130
	v_add_f32_e32 v133, 1.0, v135
	v_add_f32_e32 v135, 1.0, v137
	v_rcp_f32_e32 v130, v130
	v_rcp_f32_e32 v131, v131
	v_rcp_f32_e32 v132, v132
	v_rcp_f32_e32 v133, v133
	v_rcp_f32_e32 v137, v135
	v_rcp_f32_e32 v135, v169
	v_pk_mul_f32 v[130:131], v[30:31], v[130:131]
	v_pk_mul_f32 v[132:133], v[32:33], v[132:133]
	v_pk_mul_f32 v[136:137], v[24:25], v[136:137]
	v_pk_mul_f32 v[134:135], v[22:23], v[134:135]

; __device__ __forceinline__ float sigmoidf_(float x) { return __builtin_amdgcn_rcpf(1.f + __expf(-x)); }
; __device__ __forceinline__ float siluf_(float x) { return x * __builtin_amdgcn_rcpf(1.f + __expf(-x)); }
; __device__ __forceinline__ u32x4 pack8(const f32x4 a, const f32x4 b) { u32x4 w; w.x = cvt_pk_bf16(a[0], a[1]); w.y = cvt_pk_bf16(a[2], a[3]); w.z = cvt_pk_bf16(b[0], b[1]); w.w = cvt_pk_bf16(b[2], b[3]); return w; }
;     __device__ __forceinline__ void operator()(const f32x4 (&acc)[2][2][4][2], const Unit& u, int wr, int wc, int fr, int fq) const {
;     ...
;                 for (int m = 0; m < 4; ++m) { const int r = row0 + ai * HALF + m * 16;
;                     f32x4 v0 = acc[ai][bj][m][0], v1 = acc[ai][bj][m][1];
;                     if (mode == 1) {
; #pragma unroll
;                         for (int i = 0; i < 4; ++i) { v0[i] = siluf_(v0[i]) * QSCALE; v1[i] = siluf_(v1[i]) * QSCALE; }
;                     } else if (mode == 2) {
; #pragma unroll
;                         for (int i = 0; i < 4; ++i) { v0[i] = __logf(lb[i] + (1.f - lb[i]) * sigmoidf_(v0[i])); v1[i] = __logf(lb[4 + i] + (1.f - lb[4 + i]) * sigmoidf_(v1[i])); }
;                     } else if (mode == 3) {
; #pragma unroll
;                         for (int i = 0; i < 4; ++i) { v0[i] = siluf_(v0[i]); v1[i] = siluf_(v1[i]); }
;                     }
;                     const u32x4 w = pack8(v0, v1);
;                     *(u32x4*)(base + ((size_t)((r >> 6) * 4 + h)) * 32768 + part * 8192 + (r & 63) * 128 + c8) = w;
;                     if (grp == 1 && part < 3 && m == 3 && fr >= 13) *(u32x4*)(halo + (size_t)(r >> 6) * 4608 + (fr - 13) * 1536 + h * 384 + part * 128 + c8) = w;
.LBB0_188:
	v_mov_b32_e32 v171, v147
	v_cvt_pk_bf16_f32 v130, v130, v131
	v_cvt_pk_bf16_f32 v131, v132, v133
	v_cvt_pk_bf16_f32 v132, v134, v135
	v_cvt_pk_bf16_f32 v133, v136, v137
	v_lshl_add_u64 v[134:135], v[180:181], 0, v[170:171]
	s_and_b64 vcc, exec, s[12:13]
	s_mov_b64 s[12:13], -1
	global_store_dwordx4 v[134:135], v[130:133], off sc1
	s_cbranch_vccnz .LBB0_192
	v_mov_b64_e32 v[136:137], v[8:9]
	v_mov_b64_e32 v[132:133], v[16:17]
	s_and_b64 vcc, exec, s[10:11]
	v_mov_b64_e32 v[134:135], v[6:7]
	v_mov_b64_e32 v[130:131], v[14:15]
	s_cbranch_vccnz .LBB0_191
	v_mul_f32_e32 v131, 0xbfb8aa3b, v6
	v_mul_f32_e32 v132, 0xbfb8aa3b, v15
	v_exp_f32_e32 v131, v131
	v_exp_f32_e32 v132, v132
	v_mul_f32_e32 v133, 0xbfb8aa3b, v16
	v_mul_f32_e32 v135, 0xbfb8aa3b, v8
	v_add_f32_e32 v131, 1.0, v131
	v_rcp_f32_e32 v134, v131
	v_add_f32_e32 v131, 1.0, v132
	v_mul_f32_e32 v132, 0xbfb8aa3b, v7
	v_exp_f32_e32 v132, v132
	v_exp_f32_e32 v133, v133
	v_exp_f32_e32 v135, v135
	v_mul_f32_e32 v130, 0xbfb8aa3b, v14
	v_add_f32_e32 v169, 1.0, v132
	v_add_f32_e32 v132, 1.0, v133
	v_add_f32_e32 v133, 1.0, v135
	v_mul_f32_e32 v135, 0xbfb8aa3b, v17
	v_mul_f32_e32 v136, 0xbfb8aa3b, v9
	v_exp_f32_e32 v130, v130
	v_exp_f32_e32 v135, v135
	v_exp_f32_e32 v137, v136
	v_rcp_f32_e32 v136, v133
	v_add_f32_e32 v130, 1.0, v130
	v_add_f32_e32 v133, 1.0, v135
	v_add_f32_e32 v135, 1.0, v137
	v_rcp_f32_e32 v130, v130
	v_rcp_f32_e32 v131, v131
	v_rcp_f32_e32 v132, v132
	v_rcp_f32_e32 v133, v133
	v_rcp_f32_e32 v137, v135
	v_rcp_f32_e32 v135, v169
	v_pk_mul_f32 v[130:131], v[14:15], v[130:131]
	v_pk_mul_f32 v[132:133], v[16:17], v[132:133]
	v_pk_mul_f32 v[136:137], v[8:9], v[136:137]
	v_pk_mul_f32 v[134:135], v[6:7], v[134:135]

; __device__ __forceinline__ u32x4 pack8(const f32x4 a, const f32x4 b) { u32x4 w; w.x = cvt_pk_bf16(a[0], a[1]); w.y = cvt_pk_bf16(a[2], a[3]); w.z = cvt_pk_bf16(b[0], b[1]); w.w = cvt_pk_bf16(b[2], b[3]); return w; }
;     __device__ __forceinline__ void operator()(const f32x4 (&acc)[2][2][4][2], const Unit& u, int wr, int wc, int fr, int fq) const {
;     ...
;                     const u32x4 w = pack8(v0, v1);
;                     *(u32x4*)(base + ((size_t)((r >> 6) * 4 + h)) * 32768 + part * 8192 + (r & 63) * 128 + c8) = w;
;                     if (grp == 1 && part < 3 && m == 3 && fr >= 13) *(u32x4*)(halo + (size_t)(r >> 6) * 4608 + (fr - 13) * 1536 + h * 384 + part * 128 + c8) = w;
.LBB0_194:
	s_ashr_i32 s10, s38, 6
	v_mov_b32_e32 v169, v147
	s_mul_hi_i32 s11, s10, 0x2400
	s_mulk_i32 s10, 0x2400
	v_cvt_pk_bf16_f32 v130, v130, v131
	v_cvt_pk_bf16_f32 v131, v132, v133
	v_cvt_pk_bf16_f32 v132, v134, v135
	v_cvt_pk_bf16_f32 v133, v136, v137
	v_lshl_add_u64 v[134:135], v[180:181], 0, v[168:169]
	global_store_dwordx4 v[134:135], v[130:133], off sc1
	v_lshl_add_u64 v[134:135], v[156:157], 0, s[10:11]
	s_and_saveexec_b64 s[10:11], s[78:79]
	s_cbranch_execz .LBB0_196
	v_lshl_add_u64 v[136:137], s[76:77], 1, v[134:135]
	s_lshl_b32 s38, s4, 1
	v_lshl_add_u64 v[136:137], v[136:137], 0, s[38:39]
	v_lshl_add_u64 v[136:137], v[136:137], 0, v[146:147]
	v_add_co_u32_e32 v136, vcc, 0xffff7000, v136
	s_nop 1
	v_addc_co_u32_e32 v137, vcc, -1, v137, vcc
	global_store_dwordx4 v[136:137], v[130:133], off offset:-3072 sc1

; __device__ __forceinline__ float sigmoidf_(float x) { return __builtin_amdgcn_rcpf(1.f + __expf(-x)); }
; __device__ __forceinline__ float siluf_(float x) { return x * __builtin_amdgcn_rcpf(1.f + __expf(-x)); }
; __device__ __forceinline__ u32x4 pack8(const f32x4 a, const f32x4 b) { u32x4 w; w.x = cvt_pk_bf16(a[0], a[1]); w.y = cvt_pk_bf16(a[2], a[3]); w.z = cvt_pk_bf16(b[0], b[1]); w.w = cvt_pk_bf16(b[2], b[3]); return w; }
;     __device__ __forceinline__ void operator()(const f32x4 (&acc)[2][2][4][2], const Unit& u, int wr, int wc, int fr, int fq) const {
;     ...
;                 for (int m = 0; m < 4; ++m) { const int r = row0 + ai * HALF + m * 16;
;                     f32x4 v0 = acc[ai][bj][m][0], v1 = acc[ai][bj][m][1];
;                     if (mode == 1) {
; #pragma unroll
;                         for (int i = 0; i < 4; ++i) { v0[i] = siluf_(v0[i]) * QSCALE; v1[i] = siluf_(v1[i]) * QSCALE; }
;                     } else if (mode == 2) {
; #pragma unroll
;                         for (int i = 0; i < 4; ++i) { v0[i] = __logf(lb[i] + (1.f - lb[i]) * sigmoidf_(v0[i])); v1[i] = __logf(lb[4 + i] + (1.f - lb[4 + i]) * sigmoidf_(v1[i])); }
;                     } else if (mode == 3) {
; #pragma unroll
;                         for (int i = 0; i < 4; ++i) { v0[i] = siluf_(v0[i]); v1[i] = siluf_(v1[i]); }
;                     }
;                     const u32x4 w = pack8(v0, v1);
;                     *(u32x4*)(base + ((size_t)((r >> 6) * 4 + h)) * 32768 + part * 8192 + (r & 63) * 128 + c8) = w;
;                     if (grp == 1 && part < 3 && m == 3 && fr >= 13) *(u32x4*)(halo + (size_t)(r >> 6) * 4608 + (fr - 13) * 1536 + h * 384 + part * 128 + c8) = w;
.LBB0_211:
	s_add_i32 s14, s51, s33
	s_lshl_b32 s38, s74, 14
	s_ashr_i32 s15, s14, 31
	v_lshl_add_u64 v[136:137], v[178:179], 0, s[38:39]
	s_lshl_b64 s[14:15], s[14:15], 16
	v_lshl_add_u64 v[178:179], v[136:137], 0, s[14:15]
	v_mov_b32_e32 v175, v147
	v_cvt_pk_bf16_f32 v130, v130, v131
	v_cvt_pk_bf16_f32 v131, v180, v181
	v_cvt_pk_bf16_f32 v132, v132, v133
	v_cvt_pk_bf16_f32 v133, v182, v183
	v_lshl_add_u64 v[180:181], v[178:179], 0, v[174:175]
	s_and_b64 vcc, exec, s[12:13]
	s_mov_b64 s[14:15], -1
	global_store_dwordx4 v[180:181], v[130:133], off sc1
	s_cbranch_vccnz .LBB0_215
	s_and_b64 vcc, exec, s[10:11]
	v_mov_b32_e32 v183, v101
	v_mov_b32_e32 v182, v100
	v_mov_b32_e32 v133, v99
	v_mov_b32_e32 v132, v98
	v_mov_b32_e32 v181, v109
	v_mov_b32_e32 v180, v108
	v_mov_b32_e32 v131, v107
	v_mov_b32_e32 v130, v106
	s_cbranch_vccnz .LBB0_214
	v_mul_f32_e32 v169, 0xbfb8aa3b, v108
	v_mul_f32_e32 v131, 0xbfb8aa3b, v98
	v_exp_f32_e32 v169, v169
	v_mul_f32_e32 v171, 0xbfb8aa3b, v100
	v_mul_f32_e32 v132, 0xbfb8aa3b, v107
	v_exp_f32_e32 v131, v131
	v_exp_f32_e32 v171, v171
	v_exp_f32_e32 v133, v132
	v_add_f32_e32 v169, 1.0, v169
	v_add_f32_e32 v131, 1.0, v131
	v_rcp_f32_e32 v180, v169
	v_add_f32_e32 v169, 1.0, v171
	v_mul_f32_e32 v171, 0xbfb8aa3b, v109
	v_mul_f32_e32 v130, 0xbfb8aa3b, v106
	v_rcp_f32_e32 v132, v131
	v_add_f32_e32 v131, 1.0, v133
	v_mul_f32_e32 v133, 0xbfb8aa3b, v99
	v_exp_f32_e32 v171, v171
	v_mul_f32_e32 v173, 0xbfb8aa3b, v101
	v_exp_f32_e32 v130, v130
	v_exp_f32_e32 v133, v133
	v_exp_f32_e32 v173, v173
	v_rcp_f32_e32 v182, v169
	v_add_f32_e32 v169, 1.0, v171
	v_add_f32_e32 v130, 1.0, v130
	v_add_f32_e32 v133, 1.0, v133
	v_rcp_f32_e32 v181, v169
	v_add_f32_e32 v169, 1.0, v173
	v_rcp_f32_e32 v130, v130
	v_rcp_f32_e32 v131, v131
	v_rcp_f32_e32 v183, v169
	v_rcp_f32_e32 v133, v133
	v_pk_mul_f32 v[180:181], v[108:109], v[180:181]
	v_pk_mul_f32 v[130:131], v[106:107], v[130:131]
	v_pk_mul_f32 v[182:183], v[100:101], v[182:183]
	v_pk_mul_f32 v[132:133], v[98:99], v[132:133]

; __device__ __forceinline__ float sigmoidf_(float x) { return __builtin_amdgcn_rcpf(1.f + __expf(-x)); }
; __device__ __forceinline__ float siluf_(float x) { return x * __builtin_amdgcn_rcpf(1.f + __expf(-x)); }
; __device__ __forceinline__ u32x4 pack8(const f32x4 a, const f32x4 b) { u32x4 w; w.x = cvt_pk_bf16(a[0], a[1]); w.y = cvt_pk_bf16(a[2], a[3]); w.z = cvt_pk_bf16(b[0], b[1]); w.w = cvt_pk_bf16(b[2], b[3]); return w; }
;     __device__ __forceinline__ void operator()(const f32x4 (&acc)[2][2][4][2], const Unit& u, int wr, int wc, int fr, int fq) const {
;     ...
;                 for (int m = 0; m < 4; ++m) { const int r = row0 + ai * HALF + m * 16;
;                     f32x4 v0 = acc[ai][bj][m][0], v1 = acc[ai][bj][m][1];
;                     if (mode == 1) {
; #pragma unroll
;                         for (int i = 0; i < 4; ++i) { v0[i] = siluf_(v0[i]) * QSCALE; v1[i] = siluf_(v1[i]) * QSCALE; }
;                     } else if (mode == 2) {
; #pragma unroll
;                         for (int i = 0; i < 4; ++i) { v0[i] = __logf(lb[i] + (1.f - lb[i]) * sigmoidf_(v0[i])); v1[i] = __logf(lb[4 + i] + (1.f - lb[4 + i]) * sigmoidf_(v1[i])); }
;                     } else if (mode == 3) {
; #pragma unroll
;                         for (int i = 0; i < 4; ++i) { v0[i] = siluf_(v0[i]); v1[i] = siluf_(v1[i]); }
;                     }
;                     const u32x4 w = pack8(v0, v1);
;                     *(u32x4*)(base + ((size_t)((r >> 6) * 4 + h)) * 32768 + part * 8192 + (r & 63) * 128 + c8) = w;
;                     if (grp == 1 && part < 3 && m == 3 && fr >= 13) *(u32x4*)(halo + (size_t)(r >> 6) * 4608 + (fr - 13) * 1536 + h * 384 + part * 128 + c8) = w;
.LBB0_217:
	v_mov_b32_e32 v173, v147
	v_cvt_pk_bf16_f32 v130, v130, v131
	v_cvt_pk_bf16_f32 v131, v180, v181
	v_cvt_pk_bf16_f32 v132, v132, v133
	v_cvt_pk_bf16_f32 v133, v182, v183
	v_lshl_add_u64 v[180:181], v[178:179], 0, v[172:173]
	s_and_b64 vcc, exec, s[12:13]
	s_mov_b64 s[14:15], -1
	global_store_dwordx4 v[180:181], v[130:133], off sc1
	s_cbranch_vccnz .LBB0_221
	s_and_b64 vcc, exec, s[10:11]
	v_mov_b32_e32 v183, v85
	v_mov_b32_e32 v182, v84
	v_mov_b32_e32 v133, v83
	v_mov_b32_e32 v132, v82
	v_mov_b32_e32 v181, v93
	v_mov_b32_e32 v180, v92
	v_mov_b32_e32 v131, v91
	v_mov_b32_e32 v130, v90
	s_cbranch_vccnz .LBB0_220
	v_mul_f32_e32 v169, 0xbfb8aa3b, v92
	v_mul_f32_e32 v131, 0xbfb8aa3b, v82
	v_exp_f32_e32 v169, v169
	v_mul_f32_e32 v171, 0xbfb8aa3b, v84
	v_mul_f32_e32 v132, 0xbfb8aa3b, v91
	v_exp_f32_e32 v131, v131
	v_exp_f32_e32 v171, v171
	v_exp_f32_e32 v133, v132
	v_add_f32_e32 v169, 1.0, v169
	v_add_f32_e32 v131, 1.0, v131
	v_rcp_f32_e32 v180, v169
	v_add_f32_e32 v169, 1.0, v171
	v_mul_f32_e32 v171, 0xbfb8aa3b, v93
	v_mul_f32_e32 v130, 0xbfb8aa3b, v90
	v_rcp_f32_e32 v132, v131
	v_add_f32_e32 v131, 1.0, v133
	v_mul_f32_e32 v133, 0xbfb8aa3b, v83
	v_exp_f32_e32 v171, v171
	v_mul_f32_e32 v173, 0xbfb8aa3b, v85
	v_exp_f32_e32 v130, v130
	v_exp_f32_e32 v133, v133
	v_exp_f32_e32 v173, v173
	v_rcp_f32_e32 v182, v169
	v_add_f32_e32 v169, 1.0, v171
	v_add_f32_e32 v130, 1.0, v130
	v_add_f32_e32 v133, 1.0, v133
	v_rcp_f32_e32 v181, v169
	v_add_f32_e32 v169, 1.0, v173
	v_rcp_f32_e32 v130, v130
	v_rcp_f32_e32 v131, v131
	v_rcp_f32_e32 v183, v169
	v_rcp_f32_e32 v133, v133
	v_pk_mul_f32 v[180:181], v[92:93], v[180:181]
	v_pk_mul_f32 v[130:131], v[90:91], v[130:131]
	v_pk_mul_f32 v[182:183], v[84:85], v[182:183]
	v_pk_mul_f32 v[132:133], v[82:83], v[132:133]

; __device__ __forceinline__ float sigmoidf_(float x) { return __builtin_amdgcn_rcpf(1.f + __expf(-x)); }
; __device__ __forceinline__ float siluf_(float x) { return x * __builtin_amdgcn_rcpf(1.f + __expf(-x)); }
; __device__ __forceinline__ u32x4 pack8(const f32x4 a, const f32x4 b) { u32x4 w; w.x = cvt_pk_bf16(a[0], a[1]); w.y = cvt_pk_bf16(a[2], a[3]); w.z = cvt_pk_bf16(b[0], b[1]); w.w = cvt_pk_bf16(b[2], b[3]); return w; }
;     __device__ __forceinline__ void operator()(const f32x4 (&acc)[2][2][4][2], const Unit& u, int wr, int wc, int fr, int fq) const {
;     ...
;                 for (int m = 0; m < 4; ++m) { const int r = row0 + ai * HALF + m * 16;
;                     f32x4 v0 = acc[ai][bj][m][0], v1 = acc[ai][bj][m][1];
;                     if (mode == 1) {
; #pragma unroll
;                         for (int i = 0; i < 4; ++i) { v0[i] = siluf_(v0[i]) * QSCALE; v1[i] = siluf_(v1[i]) * QSCALE; }
;                     } else if (mode == 2) {
; #pragma unroll
;                         for (int i = 0; i < 4; ++i) { v0[i] = __logf(lb[i] + (1.f - lb[i]) * sigmoidf_(v0[i])); v1[i] = __logf(lb[4 + i] + (1.f - lb[4 + i]) * sigmoidf_(v1[i])); }
;                     } else if (mode == 3) {
; #pragma unroll
;                         for (int i = 0; i < 4; ++i) { v0[i] = siluf_(v0[i]); v1[i] = siluf_(v1[i]); }
;                     }
;                     const u32x4 w = pack8(v0, v1);
;                     *(u32x4*)(base + ((size_t)((r >> 6) * 4 + h)) * 32768 + part * 8192 + (r & 63) * 128 + c8) = w;
;                     if (grp == 1 && part < 3 && m == 3 && fr >= 13) *(u32x4*)(halo + (size_t)(r >> 6) * 4608 + (fr - 13) * 1536 + h * 384 + part * 128 + c8) = w;
.LBB0_223:
	v_mov_b32_e32 v171, v147
	v_cvt_pk_bf16_f32 v130, v130, v131
	v_cvt_pk_bf16_f32 v131, v180, v181
	v_cvt_pk_bf16_f32 v132, v132, v133
	v_cvt_pk_bf16_f32 v133, v182, v183
	v_lshl_add_u64 v[180:181], v[178:179], 0, v[170:171]
	s_and_b64 vcc, exec, s[12:13]
	s_mov_b64 s[14:15], -1
	global_store_dwordx4 v[180:181], v[130:133], off sc1
	s_cbranch_vccnz .LBB0_227
	s_and_b64 vcc, exec, s[10:11]
	v_mov_b32_e32 v183, v69
	v_mov_b32_e32 v182, v68
	v_mov_b32_e32 v133, v67
	v_mov_b32_e32 v132, v66
	v_mov_b32_e32 v181, v77
	v_mov_b32_e32 v180, v76
	v_mov_b32_e32 v131, v75
	v_mov_b32_e32 v130, v74
	s_cbranch_vccnz .LBB0_226
	v_mul_f32_e32 v169, 0xbfb8aa3b, v76
	v_mul_f32_e32 v131, 0xbfb8aa3b, v66
	v_exp_f32_e32 v169, v169
	v_mul_f32_e32 v171, 0xbfb8aa3b, v68
	v_mul_f32_e32 v132, 0xbfb8aa3b, v75
	v_exp_f32_e32 v131, v131
	v_exp_f32_e32 v171, v171
	v_exp_f32_e32 v133, v132
	v_add_f32_e32 v169, 1.0, v169
	v_add_f32_e32 v131, 1.0, v131
	v_rcp_f32_e32 v180, v169
	v_add_f32_e32 v169, 1.0, v171
	v_mul_f32_e32 v171, 0xbfb8aa3b, v77
	v_mul_f32_e32 v130, 0xbfb8aa3b, v74
	v_rcp_f32_e32 v132, v131
	v_add_f32_e32 v131, 1.0, v133
	v_mul_f32_e32 v133, 0xbfb8aa3b, v67
	v_exp_f32_e32 v171, v171
	v_mul_f32_e32 v173, 0xbfb8aa3b, v69
	v_exp_f32_e32 v130, v130
	v_exp_f32_e32 v133, v133
	v_exp_f32_e32 v173, v173
	v_rcp_f32_e32 v182, v169
	v_add_f32_e32 v169, 1.0, v171
	v_add_f32_e32 v130, 1.0, v130
	v_add_f32_e32 v133, 1.0, v133
	v_rcp_f32_e32 v181, v169
	v_add_f32_e32 v169, 1.0, v173
	v_rcp_f32_e32 v130, v130
	v_rcp_f32_e32 v131, v131
	v_rcp_f32_e32 v183, v169
	v_rcp_f32_e32 v133, v133
	v_pk_mul_f32 v[180:181], v[76:77], v[180:181]
	v_pk_mul_f32 v[130:131], v[74:75], v[130:131]
	v_pk_mul_f32 v[182:183], v[68:69], v[182:183]
	v_pk_mul_f32 v[132:133], v[66:67], v[132:133]

; __device__ __forceinline__ u32x4 pack8(const f32x4 a, const f32x4 b) { u32x4 w; w.x = cvt_pk_bf16(a[0], a[1]); w.y = cvt_pk_bf16(a[2], a[3]); w.z = cvt_pk_bf16(b[0], b[1]); w.w = cvt_pk_bf16(b[2], b[3]); return w; }
;     __device__ __forceinline__ void operator()(const f32x4 (&acc)[2][2][4][2], const Unit& u, int wr, int wc, int fr, int fq) const {
;     ...
;                     const u32x4 w = pack8(v0, v1);
;                     *(u32x4*)(base + ((size_t)((r >> 6) * 4 + h)) * 32768 + part * 8192 + (r & 63) * 128 + c8) = w;
;                     if (grp == 1 && part < 3 && m == 3 && fr >= 13) *(u32x4*)(halo + (size_t)(r >> 6) * 4608 + (fr - 13) * 1536 + h * 384 + part * 128 + c8) = w;
.LBB0_229:
	s_and_b64 s[14:15], s[16:17], s[70:71]
	s_mul_i32 s70, s51, 0x180
	v_mov_b32_e32 v169, v147
	s_ashr_i32 s71, s70, 31
	s_lshl_b32 s74, s74, 7
	v_cvt_pk_bf16_f32 v130, v130, v131
	v_cvt_pk_bf16_f32 v131, v180, v181
	v_cvt_pk_bf16_f32 v132, v132, v133
	v_cvt_pk_bf16_f32 v133, v182, v183
	v_lshl_add_u64 v[178:179], v[178:179], 0, v[168:169]
	s_and_b64 s[72:73], s[14:15], s[6:7]
	global_store_dwordx4 v[178:179], v[130:133], off sc1
	s_and_saveexec_b64 s[14:15], s[72:73]
	s_cbranch_execz .LBB0_231
	v_lshl_add_u64 v[176:177], s[70:71], 1, v[176:177]
	s_lshl_b32 s38, s74, 1
	v_lshl_add_u64 v[176:177], v[176:177], 0, s[38:39]
	v_lshl_add_u64 v[176:177], v[176:177], 0, v[146:147]
	v_add_co_u32_e32 v176, vcc, 0xffff7000, v176
	s_nop 1
	v_addc_co_u32_e32 v177, vcc, -1, v177, vcc
	global_store_dwordx4 v[176:177], v[130:133], off offset:-3072 sc1

; __device__ __forceinline__ float sigmoidf_(float x) { return __builtin_amdgcn_rcpf(1.f + __expf(-x)); }
; __device__ __forceinline__ float siluf_(float x) { return x * __builtin_amdgcn_rcpf(1.f + __expf(-x)); }
; __device__ __forceinline__ u32x4 pack8(const f32x4 a, const f32x4 b) { u32x4 w; w.x = cvt_pk_bf16(a[0], a[1]); w.y = cvt_pk_bf16(a[2], a[3]); w.z = cvt_pk_bf16(b[0], b[1]); w.w = cvt_pk_bf16(b[2], b[3]); return w; }
;     __device__ __forceinline__ void operator()(const f32x4 (&acc)[2][2][4][2], const Unit& u, int wr, int wc, int fr, int fq) const {
;     ...
;                 for (int m = 0; m < 4; ++m) { const int r = row0 + ai * HALF + m * 16;
;                     f32x4 v0 = acc[ai][bj][m][0], v1 = acc[ai][bj][m][1];
;                     if (mode == 1) {
; #pragma unroll
;                         for (int i = 0; i < 4; ++i) { v0[i] = siluf_(v0[i]) * QSCALE; v1[i] = siluf_(v1[i]) * QSCALE; }
;                     } else if (mode == 2) {
; #pragma unroll
;                         for (int i = 0; i < 4; ++i) { v0[i] = __logf(lb[i] + (1.f - lb[i]) * sigmoidf_(v0[i])); v1[i] = __logf(lb[4 + i] + (1.f - lb[4 + i]) * sigmoidf_(v1[i])); }
;                     } else if (mode == 3) {
; #pragma unroll
;                         for (int i = 0; i < 4; ++i) { v0[i] = siluf_(v0[i]); v1[i] = siluf_(v1[i]); }
;                     }
;                     const u32x4 w = pack8(v0, v1);
;                     *(u32x4*)(base + ((size_t)((r >> 6) * 4 + h)) * 32768 + part * 8192 + (r & 63) * 128 + c8) = w;
;                     if (grp == 1 && part < 3 && m == 3 && fr >= 13) *(u32x4*)(halo + (size_t)(r >> 6) * 4608 + (fr - 13) * 1536 + h * 384 + part * 128 + c8) = w;
.LBB0_237:
	s_add_i32 s14, s51, s97
	s_ashr_i32 s15, s14, 31
	s_lshl_b64 s[14:15], s[14:15], 16
	v_lshl_add_u64 v[136:137], v[136:137], 0, s[14:15]
	v_mov_b32_e32 v175, v147
	v_cvt_pk_bf16_f32 v130, v130, v131
	v_cvt_pk_bf16_f32 v131, v176, v177
	v_cvt_pk_bf16_f32 v132, v132, v133
	v_cvt_pk_bf16_f32 v133, v178, v179
	v_lshl_add_u64 v[174:175], v[136:137], 0, v[174:175]
	s_and_b64 vcc, exec, s[12:13]
	s_mov_b64 s[14:15], -1
	global_store_dwordx4 v[174:175], v[130:133], off sc1
	s_cbranch_vccnz .LBB0_241
	s_and_b64 vcc, exec, s[10:11]
	v_mov_b32_e32 v177, v37
	v_mov_b32_e32 v176, v36
	v_mov_b32_e32 v133, v35
	v_mov_b32_e32 v132, v34
	v_mov_b32_e32 v175, v45
	v_mov_b32_e32 v174, v44
	v_mov_b32_e32 v131, v43
	v_mov_b32_e32 v130, v42
	s_cbranch_vccnz .LBB0_240
	v_mul_f32_e32 v169, 0xbfb8aa3b, v44
	v_mul_f32_e32 v131, 0xbfb8aa3b, v34
	v_exp_f32_e32 v169, v169
	v_mul_f32_e32 v171, 0xbfb8aa3b, v36
	v_mul_f32_e32 v132, 0xbfb8aa3b, v43
	v_exp_f32_e32 v131, v131
	v_exp_f32_e32 v171, v171
	v_exp_f32_e32 v133, v132
	v_add_f32_e32 v169, 1.0, v169
	v_add_f32_e32 v131, 1.0, v131
	v_rcp_f32_e32 v174, v169
	v_add_f32_e32 v169, 1.0, v171
	v_mul_f32_e32 v171, 0xbfb8aa3b, v45
	v_mul_f32_e32 v130, 0xbfb8aa3b, v42
	v_rcp_f32_e32 v132, v131
	v_add_f32_e32 v131, 1.0, v133
	v_mul_f32_e32 v133, 0xbfb8aa3b, v35
	v_exp_f32_e32 v171, v171
	v_mul_f32_e32 v173, 0xbfb8aa3b, v37
	v_exp_f32_e32 v130, v130
	v_exp_f32_e32 v133, v133
	v_exp_f32_e32 v173, v173
	v_rcp_f32_e32 v176, v169
	v_add_f32_e32 v169, 1.0, v171
	v_add_f32_e32 v130, 1.0, v130
	v_add_f32_e32 v133, 1.0, v133
	v_rcp_f32_e32 v175, v169
	v_add_f32_e32 v169, 1.0, v173
	v_rcp_f32_e32 v130, v130
	v_rcp_f32_e32 v131, v131
	v_rcp_f32_e32 v177, v169
	v_rcp_f32_e32 v133, v133
	v_pk_mul_f32 v[174:175], v[44:45], v[174:175]
	v_pk_mul_f32 v[130:131], v[42:43], v[130:131]
	v_pk_mul_f32 v[176:177], v[36:37], v[176:177]
	v_pk_mul_f32 v[132:133], v[34:35], v[132:133]

; __device__ __forceinline__ float sigmoidf_(float x) { return __builtin_amdgcn_rcpf(1.f + __expf(-x)); }
; __device__ __forceinline__ float siluf_(float x) { return x * __builtin_amdgcn_rcpf(1.f + __expf(-x)); }
; __device__ __forceinline__ u32x4 pack8(const f32x4 a, const f32x4 b) { u32x4 w; w.x = cvt_pk_bf16(a[0], a[1]); w.y = cvt_pk_bf16(a[2], a[3]); w.z = cvt_pk_bf16(b[0], b[1]); w.w = cvt_pk_bf16(b[2], b[3]); return w; }
;     __device__ __forceinline__ void operator()(const f32x4 (&acc)[2][2][4][2], const Unit& u, int wr, int wc, int fr, int fq) const {
;     ...
;                 for (int m = 0; m < 4; ++m) { const int r = row0 + ai * HALF + m * 16;
;                     f32x4 v0 = acc[ai][bj][m][0], v1 = acc[ai][bj][m][1];
;                     if (mode == 1) {
; #pragma unroll
;                         for (int i = 0; i < 4; ++i) { v0[i] = siluf_(v0[i]) * QSCALE; v1[i] = siluf_(v1[i]) * QSCALE; }
;                     } else if (mode == 2) {
; #pragma unroll
;                         for (int i = 0; i < 4; ++i) { v0[i] = __logf(lb[i] + (1.f - lb[i]) * sigmoidf_(v0[i])); v1[i] = __logf(lb[4 + i] + (1.f - lb[4 + i]) * sigmoidf_(v1[i])); }
;                     } else if (mode == 3) {
; #pragma unroll
;                         for (int i = 0; i < 4; ++i) { v0[i] = siluf_(v0[i]); v1[i] = siluf_(v1[i]); }
;                     }
;                     const u32x4 w = pack8(v0, v1);
;                     *(u32x4*)(base + ((size_t)((r >> 6) * 4 + h)) * 32768 + part * 8192 + (r & 63) * 128 + c8) = w;
;                     if (grp == 1 && part < 3 && m == 3 && fr >= 13) *(u32x4*)(halo + (size_t)(r >> 6) * 4608 + (fr - 13) * 1536 + h * 384 + part * 128 + c8) = w;
.LBB0_243:
	v_mov_b32_e32 v173, v147
	v_cvt_pk_bf16_f32 v130, v130, v131
	v_cvt_pk_bf16_f32 v131, v174, v175
	v_cvt_pk_bf16_f32 v132, v132, v133
	v_cvt_pk_bf16_f32 v133, v176, v177
	v_lshl_add_u64 v[172:173], v[136:137], 0, v[172:173]
	s_and_b64 vcc, exec, s[12:13]
	s_mov_b64 s[14:15], -1
	global_store_dwordx4 v[172:173], v[130:133], off sc1
	s_cbranch_vccnz .LBB0_247
	s_and_b64 vcc, exec, s[10:11]
	v_mov_b32_e32 v175, v21
	v_mov_b32_e32 v174, v20
	v_mov_b32_e32 v133, v19
	v_mov_b32_e32 v132, v18
	v_mov_b32_e32 v173, v29
	v_mov_b32_e32 v172, v28
	v_mov_b32_e32 v131, v27
	v_mov_b32_e32 v130, v26
	s_cbranch_vccnz .LBB0_246
	v_mul_f32_e32 v169, 0xbfb8aa3b, v28
	v_mul_f32_e32 v131, 0xbfb8aa3b, v18
	v_exp_f32_e32 v169, v169
	v_mul_f32_e32 v171, 0xbfb8aa3b, v20
	v_mul_f32_e32 v132, 0xbfb8aa3b, v27
	v_exp_f32_e32 v131, v131
	v_exp_f32_e32 v171, v171
	v_exp_f32_e32 v133, v132
	v_add_f32_e32 v169, 1.0, v169
	v_add_f32_e32 v131, 1.0, v131
	v_rcp_f32_e32 v172, v169
	v_add_f32_e32 v169, 1.0, v171
	v_mul_f32_e32 v171, 0xbfb8aa3b, v29
	v_mul_f32_e32 v130, 0xbfb8aa3b, v26
	v_rcp_f32_e32 v132, v131
	v_add_f32_e32 v131, 1.0, v133
	v_mul_f32_e32 v133, 0xbfb8aa3b, v19
	v_exp_f32_e32 v171, v171
	v_mul_f32_e32 v173, 0xbfb8aa3b, v21
	v_exp_f32_e32 v130, v130
	v_exp_f32_e32 v133, v133
	v_exp_f32_e32 v175, v173
	v_rcp_f32_e32 v174, v169
	v_add_f32_e32 v169, 1.0, v171
	v_add_f32_e32 v130, 1.0, v130
	v_add_f32_e32 v133, 1.0, v133
	v_rcp_f32_e32 v173, v169
	v_add_f32_e32 v169, 1.0, v175
	v_rcp_f32_e32 v130, v130
	v_rcp_f32_e32 v131, v131
	v_rcp_f32_e32 v175, v169
	v_rcp_f32_e32 v133, v133
	v_pk_mul_f32 v[172:173], v[28:29], v[172:173]
	v_pk_mul_f32 v[130:131], v[26:27], v[130:131]
	v_pk_mul_f32 v[174:175], v[20:21], v[174:175]
	v_pk_mul_f32 v[132:133], v[18:19], v[132:133]

; __device__ __forceinline__ float sigmoidf_(float x) { return __builtin_amdgcn_rcpf(1.f + __expf(-x)); }
; __device__ __forceinline__ float siluf_(float x) { return x * __builtin_amdgcn_rcpf(1.f + __expf(-x)); }
; __device__ __forceinline__ u32x4 pack8(const f32x4 a, const f32x4 b) { u32x4 w; w.x = cvt_pk_bf16(a[0], a[1]); w.y = cvt_pk_bf16(a[2], a[3]); w.z = cvt_pk_bf16(b[0], b[1]); w.w = cvt_pk_bf16(b[2], b[3]); return w; }
;     __device__ __forceinline__ void operator()(const f32x4 (&acc)[2][2][4][2], const Unit& u, int wr, int wc, int fr, int fq) const {
;     ...
;                 for (int m = 0; m < 4; ++m) { const int r = row0 + ai * HALF + m * 16;
;                     f32x4 v0 = acc[ai][bj][m][0], v1 = acc[ai][bj][m][1];
;                     if (mode == 1) {
; #pragma unroll
;                         for (int i = 0; i < 4; ++i) { v0[i] = siluf_(v0[i]) * QSCALE; v1[i] = siluf_(v1[i]) * QSCALE; }
;                     } else if (mode == 2) {
; #pragma unroll
;                         for (int i = 0; i < 4; ++i) { v0[i] = __logf(lb[i] + (1.f - lb[i]) * sigmoidf_(v0[i])); v1[i] = __logf(lb[4 + i] + (1.f - lb[4 + i]) * sigmoidf_(v1[i])); }
;                     } else if (mode == 3) {
; #pragma unroll
;                         for (int i = 0; i < 4; ++i) { v0[i] = siluf_(v0[i]); v1[i] = siluf_(v1[i]); }
;                     }
;                     const u32x4 w = pack8(v0, v1);
;                     *(u32x4*)(base + ((size_t)((r >> 6) * 4 + h)) * 32768 + part * 8192 + (r & 63) * 128 + c8) = w;
;                     if (grp == 1 && part < 3 && m == 3 && fr >= 13) *(u32x4*)(halo + (size_t)(r >> 6) * 4608 + (fr - 13) * 1536 + h * 384 + part * 128 + c8) = w;
.LBB0_249:
	v_mov_b32_e32 v171, v147
	v_cvt_pk_bf16_f32 v130, v130, v131
	v_cvt_pk_bf16_f32 v131, v172, v173
	v_cvt_pk_bf16_f32 v132, v132, v133
	v_cvt_pk_bf16_f32 v133, v174, v175
	v_lshl_add_u64 v[170:171], v[136:137], 0, v[170:171]
	s_and_b64 vcc, exec, s[12:13]
	s_mov_b64 s[12:13], -1
	global_store_dwordx4 v[170:171], v[130:133], off sc1
	s_cbranch_vccnz .LBB0_253
	s_and_b64 vcc, exec, s[10:11]
	v_mov_b32_e32 v173, v5
	v_mov_b32_e32 v172, v4
	v_mov_b32_e32 v133, v3
	v_mov_b32_e32 v132, v2
	v_mov_b32_e32 v171, v13
	v_mov_b32_e32 v170, v12
	v_mov_b32_e32 v131, v11
	v_mov_b32_e32 v130, v10
	s_cbranch_vccnz .LBB0_252
	v_mul_f32_e32 v169, 0xbfb8aa3b, v12
	v_mul_f32_e32 v131, 0xbfb8aa3b, v2
	v_exp_f32_e32 v169, v169
	v_mul_f32_e32 v170, 0xbfb8aa3b, v4
	v_mul_f32_e32 v132, 0xbfb8aa3b, v11
	v_exp_f32_e32 v131, v131
	v_exp_f32_e32 v171, v170
	v_exp_f32_e32 v133, v132
	v_add_f32_e32 v169, 1.0, v169
	v_add_f32_e32 v131, 1.0, v131
	v_rcp_f32_e32 v170, v169
	v_add_f32_e32 v169, 1.0, v171
	v_mul_f32_e32 v171, 0xbfb8aa3b, v13
	v_mul_f32_e32 v130, 0xbfb8aa3b, v10
	v_rcp_f32_e32 v132, v131
	v_add_f32_e32 v131, 1.0, v133
	v_mul_f32_e32 v133, 0xbfb8aa3b, v3
	v_exp_f32_e32 v171, v171
	v_mul_f32_e32 v172, 0xbfb8aa3b, v5
	v_exp_f32_e32 v130, v130
	v_exp_f32_e32 v133, v133
	v_exp_f32_e32 v173, v172
	v_rcp_f32_e32 v172, v169
	v_add_f32_e32 v169, 1.0, v171
	v_add_f32_e32 v130, 1.0, v130
	v_add_f32_e32 v133, 1.0, v133
	v_rcp_f32_e32 v171, v169
	v_add_f32_e32 v169, 1.0, v173
	v_rcp_f32_e32 v130, v130
	v_rcp_f32_e32 v131, v131
	v_rcp_f32_e32 v173, v169
	v_rcp_f32_e32 v133, v133
	v_pk_mul_f32 v[170:171], v[12:13], v[170:171]
	v_pk_mul_f32 v[130:131], v[10:11], v[130:131]
	v_pk_mul_f32 v[172:173], v[4:5], v[172:173]
	v_pk_mul_f32 v[132:133], v[2:3], v[132:133]

; __device__ __forceinline__ u32x4 pack8(const f32x4 a, const f32x4 b) { u32x4 w; w.x = cvt_pk_bf16(a[0], a[1]); w.y = cvt_pk_bf16(a[2], a[3]); w.z = cvt_pk_bf16(b[0], b[1]); w.w = cvt_pk_bf16(b[2], b[3]); return w; }
;     __device__ __forceinline__ void operator()(const f32x4 (&acc)[2][2][4][2], const Unit& u, int wr, int wc, int fr, int fq) const {
;     ...
;                     const u32x4 w = pack8(v0, v1);
;                     *(u32x4*)(base + ((size_t)((r >> 6) * 4 + h)) * 32768 + part * 8192 + (r & 63) * 128 + c8) = w;
;                     if (grp == 1 && part < 3 && m == 3 && fr >= 13) *(u32x4*)(halo + (size_t)(r >> 6) * 4608 + (fr - 13) * 1536 + h * 384 + part * 128 + c8) = w;
.LBB0_255:
	v_mov_b32_e32 v169, v147
	v_cvt_pk_bf16_f32 v130, v130, v131
	v_cvt_pk_bf16_f32 v131, v170, v171
	v_cvt_pk_bf16_f32 v132, v132, v133
	v_cvt_pk_bf16_f32 v133, v172, v173
	v_lshl_add_u64 v[136:137], v[136:137], 0, v[168:169]
	global_store_dwordx4 v[136:137], v[130:133], off sc1
	s_and_saveexec_b64 s[10:11], s[72:73]
	s_cbranch_execz .LBB0_257
	v_lshl_add_u64 v[134:135], s[70:71], 1, v[134:135]
	s_lshl_b32 s38, s74, 1
	v_lshl_add_u64 v[134:135], v[134:135], 0, s[38:39]
	v_lshl_add_u64 v[134:135], v[134:135], 0, v[146:147]
	v_add_co_u32_e32 v134, vcc, 0xffff7000, v134
	s_nop 1
	v_addc_co_u32_e32 v135, vcc, -1, v135, vcc
	global_store_dwordx4 v[134:135], v[130:133], off offset:-3072 sc1
